# GEMM epilogue output stores made write-through (sc1) so the grid barrier buffer_wbl2 has little to write back
# baseline (speedup 1.0000x reference)
.LBB0_53:
	v_lshl_or_b32 v144, s6, 7, v152
	s_sub_i32 s6, s7, s5
	v_lshl_add_u32 v155, s6, 10, v151
	ds_read2_b32 v[148:149], v155 offset1:16
	v_lshl_add_u32 v154, s7, 8, v1
	v_ashrrev_i32_e32 v145, 31, v144
	v_mov_b64_e32 v[142:143], s[80:81]
	v_mad_i64_i32 v[146:147], s[6:7], v154, s86, v[142:143]
	s_waitcnt lgkmcnt(0)
	v_pk_mul_f32 v[126:127], v[126:127], v[148:149] op_sel_hi:[1,0]
	v_pk_mul_f32 v[122:123], v[122:123], v[148:149] op_sel_hi:[1,0]
	v_pk_mul_f32 v[156:157], v[126:127], s[96:97] op_sel_hi:[1,0]
	v_exp_f32_e32 v156, v156
	v_exp_f32_e32 v157, v157
	v_pk_mul_f32 v[124:125], v[124:125], v[148:149] op_sel_hi:[1,0]
	v_pk_mul_f32 v[118:119], v[118:119], v[148:149] op_sel_hi:[1,0]
	v_pk_add_f32 v[156:157], v[156:157], 1.0 op_sel_hi:[1,0]
	v_rcp_f32_e32 v156, v156
	v_rcp_f32_e32 v157, v157
	v_pk_mul_f32 v[114:115], v[114:115], v[148:149] op_sel_hi:[1,0]
	v_pk_mul_f32 v[116:117], v[116:117], v[148:149] op_sel_hi:[1,0]
	v_lshlrev_b64 v[144:145], 1, v[144:145]
	v_pk_mul_f32 v[126:127], v[126:127], v[156:157]
	v_lshl_add_u64 v[146:147], v[146:147], 0, v[144:145]
	v_pk_mul_f32 v[122:123], v[122:123], v[126:127]
	v_pk_mul_f32 v[126:127], v[128:129], v[148:149] op_sel_hi:[1,0]
	s_mov_b64 s[28:29], -1
	v_pk_mul_f32 v[128:129], v[126:127], s[96:97] op_sel_hi:[1,0]
	v_exp_f32_e32 v128, v128
	v_exp_f32_e32 v129, v129
	s_andn2_b64 vcc, exec, s[42:43]
	v_pk_add_f32 v[128:129], v[128:129], 1.0 op_sel_hi:[1,0]
	v_rcp_f32_e32 v128, v128
	v_rcp_f32_e32 v129, v129
	s_nop 0
	v_pk_mul_f32 v[126:127], v[126:127], v[128:129]
	v_pk_mul_f32 v[124:125], v[124:125], v[126:127]
	v_pk_mul_f32 v[126:127], v[118:119], s[96:97] op_sel_hi:[1,0]
	v_exp_f32_e32 v126, v126
	v_exp_f32_e32 v127, v127
	s_nop 0
	v_pk_add_f32 v[126:127], v[126:127], 1.0 op_sel_hi:[1,0]
	v_rcp_f32_e32 v126, v126
	v_rcp_f32_e32 v127, v127
	s_nop 0
	v_pk_mul_f32 v[118:119], v[118:119], v[126:127]
	v_pk_mul_f32 v[118:119], v[114:115], v[118:119]
	v_pk_mul_f32 v[114:115], v[120:121], v[148:149] op_sel_hi:[1,0]
	v_pk_mul_f32 v[120:121], v[114:115], s[96:97] op_sel_hi:[1,0]
	v_exp_f32_e32 v120, v120
	v_exp_f32_e32 v121, v121
	s_nop 0
	v_pk_add_f32 v[120:121], v[120:121], 1.0 op_sel_hi:[1,0]
	v_rcp_f32_e32 v120, v120
	v_rcp_f32_e32 v121, v121
	s_nop 0
	v_pk_mul_f32 v[114:115], v[114:115], v[120:121]
	v_pk_mul_f32 v[120:121], v[116:117], v[114:115]
	v_cvt_pk_bf16_f32 v114, v122, v123
	v_cvt_pk_bf16_f32 v115, v124, v125
	v_cvt_pk_bf16_f32 v116, v118, v119
	v_cvt_pk_bf16_f32 v117, v120, v121
	global_store_dwordx4 v[146:147], v[114:117], off sc1
	s_nop 1
	v_mov_b32_e32 v116, v149
	v_pk_mul_f32 v[110:111], v[110:111], v[116:117] op_sel_hi:[1,0]
	v_or_b32_e32 v114, 16, v154
	v_mul_f32_e32 v117, 0xbfb8aa3b, v110
	v_exp_f32_e32 v117, v117
	v_mad_i64_i32 v[114:115], s[6:7], v114, s86, v[142:143]
	v_lshl_add_u64 v[114:115], v[114:115], 0, v[144:145]
	v_add_f32_e32 v117, 1.0, v117
	v_rcp_f32_e32 v118, v117
	v_pk_mul_f32 v[106:107], v[106:107], v[116:117] op_sel_hi:[1,0]
	v_mul_f32_e32 v117, 0xbfb8aa3b, v111
	v_exp_f32_e32 v117, v117
	s_nop 0
	v_add_f32_e32 v117, 1.0, v117
	v_rcp_f32_e32 v119, v117
	v_pk_mul_f32 v[108:109], v[108:109], v[116:117] op_sel_hi:[1,0]
	v_pk_mul_f32 v[102:103], v[102:103], v[116:117] op_sel_hi:[1,0]
	v_pk_mul_f32 v[98:99], v[98:99], v[116:117] op_sel_hi:[1,0]
	v_pk_mul_f32 v[110:111], v[110:111], v[118:119]
	v_pk_mul_f32 v[100:101], v[100:101], v[116:117] op_sel_hi:[1,0]
	v_pk_mul_f32 v[106:107], v[106:107], v[110:111]
	v_pk_mul_f32 v[110:111], v[112:113], v[116:117] op_sel_hi:[1,0]
	v_pk_mul_f32 v[112:113], v[110:111], s[96:97] op_sel_hi:[1,0]
	v_exp_f32_e32 v112, v112
	v_exp_f32_e32 v113, v113
	s_nop 0
	v_pk_add_f32 v[112:113], v[112:113], 1.0 op_sel_hi:[1,0]
	v_rcp_f32_e32 v112, v112
	v_rcp_f32_e32 v113, v113
	s_nop 0
	v_pk_mul_f32 v[110:111], v[110:111], v[112:113]
	v_pk_mul_f32 v[108:109], v[108:109], v[110:111]
	v_pk_mul_f32 v[110:111], v[102:103], s[96:97] op_sel_hi:[1,0]
	v_exp_f32_e32 v110, v110
	v_exp_f32_e32 v111, v111
	s_nop 0
	v_pk_add_f32 v[110:111], v[110:111], 1.0 op_sel_hi:[1,0]
	v_rcp_f32_e32 v110, v110
	v_rcp_f32_e32 v111, v111
	s_nop 0
	v_pk_mul_f32 v[102:103], v[102:103], v[110:111]
	v_pk_mul_f32 v[102:103], v[98:99], v[102:103]
	v_pk_mul_f32 v[98:99], v[104:105], v[116:117] op_sel_hi:[1,0]
	v_pk_mul_f32 v[104:105], v[98:99], s[96:97] op_sel_hi:[1,0]
	v_exp_f32_e32 v104, v104
	v_exp_f32_e32 v105, v105
	s_nop 0
	v_pk_add_f32 v[104:105], v[104:105], 1.0 op_sel_hi:[1,0]
	v_rcp_f32_e32 v104, v104
	v_rcp_f32_e32 v105, v105
	s_nop 0
	v_pk_mul_f32 v[98:99], v[98:99], v[104:105]
	v_pk_mul_f32 v[104:105], v[100:101], v[98:99]
	v_cvt_pk_bf16_f32 v98, v106, v107
	v_cvt_pk_bf16_f32 v99, v108, v109
	v_cvt_pk_bf16_f32 v100, v102, v103
	v_cvt_pk_bf16_f32 v101, v104, v105
	global_store_dwordx4 v[114:115], v[98:101], off sc1
	ds_read2_b32 v[100:101], v155 offset0:32 offset1:48
	s_waitcnt lgkmcnt(0)
	v_pk_mul_f32 v[94:95], v[94:95], v[100:101] op_sel_hi:[1,0]
	v_pk_mul_f32 v[102:103], v[94:95], s[96:97] op_sel_hi:[1,0]
	v_exp_f32_e32 v102, v102
	v_exp_f32_e32 v103, v103
	v_pk_mul_f32 v[90:91], v[90:91], v[100:101] op_sel_hi:[1,0]
	v_pk_mul_f32 v[92:93], v[92:93], v[100:101] op_sel_hi:[1,0]
	v_pk_add_f32 v[102:103], v[102:103], 1.0 op_sel_hi:[1,0]
	v_rcp_f32_e32 v102, v102
	v_rcp_f32_e32 v103, v103
	v_pk_mul_f32 v[86:87], v[86:87], v[100:101] op_sel_hi:[1,0]
	v_pk_mul_f32 v[82:83], v[82:83], v[100:101] op_sel_hi:[1,0]
	v_or_b32_e32 v98, 32, v154
	v_pk_mul_f32 v[94:95], v[94:95], v[102:103]
	v_pk_mul_f32 v[84:85], v[84:85], v[100:101] op_sel_hi:[1,0]
	v_pk_mul_f32 v[90:91], v[90:91], v[94:95]
	v_pk_mul_f32 v[94:95], v[96:97], v[100:101] op_sel_hi:[1,0]
	v_mad_i64_i32 v[98:99], s[6:7], v98, s86, v[142:143]
	v_pk_mul_f32 v[96:97], v[94:95], s[96:97] op_sel_hi:[1,0]
	v_exp_f32_e32 v96, v96
	v_exp_f32_e32 v97, v97
	v_lshl_add_u64 v[98:99], v[98:99], 0, v[144:145]
	v_pk_add_f32 v[96:97], v[96:97], 1.0 op_sel_hi:[1,0]
	v_rcp_f32_e32 v96, v96
	v_rcp_f32_e32 v97, v97
	s_nop 0
	v_pk_mul_f32 v[94:95], v[94:95], v[96:97]
	v_pk_mul_f32 v[92:93], v[92:93], v[94:95]
	v_pk_mul_f32 v[94:95], v[86:87], s[96:97] op_sel_hi:[1,0]
	v_exp_f32_e32 v94, v94
	v_exp_f32_e32 v95, v95
	s_nop 0
	v_pk_add_f32 v[94:95], v[94:95], 1.0 op_sel_hi:[1,0]
	v_rcp_f32_e32 v94, v94
	v_rcp_f32_e32 v95, v95
	s_nop 0
	v_pk_mul_f32 v[86:87], v[86:87], v[94:95]
	v_pk_mul_f32 v[86:87], v[82:83], v[86:87]
	v_pk_mul_f32 v[82:83], v[88:89], v[100:101] op_sel_hi:[1,0]
	v_pk_mul_f32 v[88:89], v[82:83], s[96:97] op_sel_hi:[1,0]
	v_exp_f32_e32 v88, v88
	v_exp_f32_e32 v89, v89
	s_nop 0
	v_pk_add_f32 v[88:89], v[88:89], 1.0 op_sel_hi:[1,0]
	v_rcp_f32_e32 v88, v88
	v_rcp_f32_e32 v89, v89
	s_nop 0
	v_pk_mul_f32 v[82:83], v[82:83], v[88:89]
	v_pk_mul_f32 v[88:89], v[84:85], v[82:83]
	v_cvt_pk_bf16_f32 v82, v90, v91
	v_cvt_pk_bf16_f32 v83, v92, v93
	v_cvt_pk_bf16_f32 v84, v86, v87
	v_cvt_pk_bf16_f32 v85, v88, v89
	global_store_dwordx4 v[98:99], v[82:85], off sc1
	s_nop 1
	v_mov_b32_e32 v84, v101
	v_pk_mul_f32 v[78:79], v[78:79], v[84:85] op_sel_hi:[1,0]
	v_or_b32_e32 v82, 48, v154
	v_mul_f32_e32 v85, 0xbfb8aa3b, v78
	v_exp_f32_e32 v85, v85
	v_mad_i64_i32 v[82:83], s[6:7], v82, s86, v[142:143]
	v_lshl_add_u64 v[82:83], v[82:83], 0, v[144:145]
	v_add_f32_e32 v85, 1.0, v85
	v_rcp_f32_e32 v86, v85
	v_pk_mul_f32 v[74:75], v[74:75], v[84:85] op_sel_hi:[1,0]
	v_mul_f32_e32 v85, 0xbfb8aa3b, v79
	v_exp_f32_e32 v85, v85
	s_nop 0
	v_add_f32_e32 v85, 1.0, v85
	v_rcp_f32_e32 v87, v85
	v_pk_mul_f32 v[76:77], v[76:77], v[84:85] op_sel_hi:[1,0]
	v_pk_mul_f32 v[70:71], v[70:71], v[84:85] op_sel_hi:[1,0]
	v_pk_mul_f32 v[66:67], v[66:67], v[84:85] op_sel_hi:[1,0]
	v_pk_mul_f32 v[78:79], v[78:79], v[86:87]
	v_pk_mul_f32 v[68:69], v[68:69], v[84:85] op_sel_hi:[1,0]
	v_pk_mul_f32 v[74:75], v[74:75], v[78:79]
	v_pk_mul_f32 v[78:79], v[80:81], v[84:85] op_sel_hi:[1,0]
	v_pk_mul_f32 v[80:81], v[78:79], s[96:97] op_sel_hi:[1,0]
	v_exp_f32_e32 v80, v80
	v_exp_f32_e32 v81, v81
	s_nop 0
	v_pk_add_f32 v[80:81], v[80:81], 1.0 op_sel_hi:[1,0]
	v_rcp_f32_e32 v80, v80
	v_rcp_f32_e32 v81, v81
	s_nop 0
	v_pk_mul_f32 v[78:79], v[78:79], v[80:81]
	v_pk_mul_f32 v[76:77], v[76:77], v[78:79]
	v_pk_mul_f32 v[78:79], v[70:71], s[96:97] op_sel_hi:[1,0]
	v_exp_f32_e32 v78, v78
	v_exp_f32_e32 v79, v79
	s_nop 0
	v_pk_add_f32 v[78:79], v[78:79], 1.0 op_sel_hi:[1,0]
	v_rcp_f32_e32 v78, v78
	v_rcp_f32_e32 v79, v79
	s_nop 0
	v_pk_mul_f32 v[70:71], v[70:71], v[78:79]
	v_pk_mul_f32 v[70:71], v[66:67], v[70:71]
	v_pk_mul_f32 v[66:67], v[72:73], v[84:85] op_sel_hi:[1,0]
	v_pk_mul_f32 v[72:73], v[66:67], s[96:97] op_sel_hi:[1,0]
	v_exp_f32_e32 v72, v72
	v_exp_f32_e32 v73, v73
	s_nop 0
	v_pk_add_f32 v[72:73], v[72:73], 1.0 op_sel_hi:[1,0]
	v_rcp_f32_e32 v72, v72
	v_rcp_f32_e32 v73, v73
	s_nop 0
	v_pk_mul_f32 v[66:67], v[66:67], v[72:73]
	v_pk_mul_f32 v[72:73], v[68:69], v[66:67]
	v_cvt_pk_bf16_f32 v66, v74, v75
	v_cvt_pk_bf16_f32 v67, v76, v77
	v_cvt_pk_bf16_f32 v68, v70, v71
	v_cvt_pk_bf16_f32 v69, v72, v73
	global_store_dwordx4 v[82:83], v[66:69], off sc1
	ds_read2_b32 v[68:69], v155 offset0:128 offset1:144
	s_waitcnt lgkmcnt(0)
	v_pk_mul_f32 v[62:63], v[62:63], v[68:69] op_sel_hi:[1,0]
	v_pk_mul_f32 v[70:71], v[62:63], s[96:97] op_sel_hi:[1,0]
	v_exp_f32_e32 v70, v70
	v_exp_f32_e32 v71, v71
	v_pk_mul_f32 v[58:59], v[58:59], v[68:69] op_sel_hi:[1,0]
	v_pk_mul_f32 v[60:61], v[60:61], v[68:69] op_sel_hi:[1,0]
	v_pk_add_f32 v[70:71], v[70:71], 1.0 op_sel_hi:[1,0]
	v_rcp_f32_e32 v70, v70
	v_rcp_f32_e32 v71, v71
	v_pk_mul_f32 v[54:55], v[54:55], v[68:69] op_sel_hi:[1,0]
	v_pk_mul_f32 v[50:51], v[50:51], v[68:69] op_sel_hi:[1,0]
	v_add_u32_e32 v66, 0x80, v154
	v_pk_mul_f32 v[62:63], v[62:63], v[70:71]
	v_pk_mul_f32 v[52:53], v[52:53], v[68:69] op_sel_hi:[1,0]
	v_pk_mul_f32 v[58:59], v[58:59], v[62:63]
	v_pk_mul_f32 v[62:63], v[64:65], v[68:69] op_sel_hi:[1,0]
	v_mad_i64_i32 v[66:67], s[6:7], v66, s86, v[142:143]
	v_pk_mul_f32 v[64:65], v[62:63], s[96:97] op_sel_hi:[1,0]
	v_exp_f32_e32 v64, v64
	v_exp_f32_e32 v65, v65
	v_lshl_add_u64 v[66:67], v[66:67], 0, v[144:145]
	v_pk_add_f32 v[64:65], v[64:65], 1.0 op_sel_hi:[1,0]
	v_rcp_f32_e32 v64, v64
	v_rcp_f32_e32 v65, v65
	s_nop 0
	v_pk_mul_f32 v[62:63], v[62:63], v[64:65]
	v_pk_mul_f32 v[60:61], v[60:61], v[62:63]
	v_pk_mul_f32 v[62:63], v[54:55], s[96:97] op_sel_hi:[1,0]
	v_exp_f32_e32 v62, v62
	v_exp_f32_e32 v63, v63
	s_nop 0
	v_pk_add_f32 v[62:63], v[62:63], 1.0 op_sel_hi:[1,0]
	v_rcp_f32_e32 v62, v62
	v_rcp_f32_e32 v63, v63
	s_nop 0
	v_pk_mul_f32 v[54:55], v[54:55], v[62:63]
	v_pk_mul_f32 v[54:55], v[50:51], v[54:55]
	v_pk_mul_f32 v[50:51], v[56:57], v[68:69] op_sel_hi:[1,0]
	v_pk_mul_f32 v[56:57], v[50:51], s[96:97] op_sel_hi:[1,0]
	v_exp_f32_e32 v56, v56
	v_exp_f32_e32 v57, v57
	s_nop 0
	v_pk_add_f32 v[56:57], v[56:57], 1.0 op_sel_hi:[1,0]
	v_rcp_f32_e32 v56, v56
	v_rcp_f32_e32 v57, v57
	s_nop 0
	v_pk_mul_f32 v[50:51], v[50:51], v[56:57]
	v_pk_mul_f32 v[56:57], v[52:53], v[50:51]
	v_cvt_pk_bf16_f32 v50, v58, v59
	v_cvt_pk_bf16_f32 v51, v60, v61
	v_cvt_pk_bf16_f32 v52, v54, v55
	v_cvt_pk_bf16_f32 v53, v56, v57
	global_store_dwordx4 v[66:67], v[50:53], off sc1
	s_nop 1
	v_mov_b32_e32 v52, v69
	v_pk_mul_f32 v[46:47], v[46:47], v[52:53] op_sel_hi:[1,0]
	v_add_u32_e32 v50, 0x90, v154
	v_mul_f32_e32 v53, 0xbfb8aa3b, v46
	v_exp_f32_e32 v53, v53
	v_mad_i64_i32 v[50:51], s[6:7], v50, s86, v[142:143]
	v_lshl_add_u64 v[50:51], v[50:51], 0, v[144:145]
	v_add_f32_e32 v53, 1.0, v53
	v_rcp_f32_e32 v54, v53
	v_pk_mul_f32 v[42:43], v[42:43], v[52:53] op_sel_hi:[1,0]
	v_mul_f32_e32 v53, 0xbfb8aa3b, v47
	v_exp_f32_e32 v53, v53
	s_nop 0
	v_add_f32_e32 v53, 1.0, v53
	v_rcp_f32_e32 v55, v53
	v_pk_mul_f32 v[44:45], v[44:45], v[52:53] op_sel_hi:[1,0]
	v_pk_mul_f32 v[38:39], v[38:39], v[52:53] op_sel_hi:[1,0]
	v_pk_mul_f32 v[34:35], v[34:35], v[52:53] op_sel_hi:[1,0]
	v_pk_mul_f32 v[46:47], v[46:47], v[54:55]
	v_pk_mul_f32 v[36:37], v[36:37], v[52:53] op_sel_hi:[1,0]
	v_pk_mul_f32 v[42:43], v[42:43], v[46:47]
	v_pk_mul_f32 v[46:47], v[48:49], v[52:53] op_sel_hi:[1,0]
	v_pk_mul_f32 v[48:49], v[46:47], s[96:97] op_sel_hi:[1,0]
	v_exp_f32_e32 v48, v48
	v_exp_f32_e32 v49, v49
	s_nop 0
	v_pk_add_f32 v[48:49], v[48:49], 1.0 op_sel_hi:[1,0]
	v_rcp_f32_e32 v48, v48
	v_rcp_f32_e32 v49, v49
	s_nop 0
	v_pk_mul_f32 v[46:47], v[46:47], v[48:49]
	v_pk_mul_f32 v[44:45], v[44:45], v[46:47]
	v_pk_mul_f32 v[46:47], v[38:39], s[96:97] op_sel_hi:[1,0]
	v_exp_f32_e32 v46, v46
	v_exp_f32_e32 v47, v47
	s_nop 0
	v_pk_add_f32 v[46:47], v[46:47], 1.0 op_sel_hi:[1,0]
	v_rcp_f32_e32 v46, v46
	v_rcp_f32_e32 v47, v47
	s_nop 0
	v_pk_mul_f32 v[38:39], v[38:39], v[46:47]
	v_pk_mul_f32 v[38:39], v[34:35], v[38:39]
	v_pk_mul_f32 v[34:35], v[40:41], v[52:53] op_sel_hi:[1,0]
	v_pk_mul_f32 v[40:41], v[34:35], s[96:97] op_sel_hi:[1,0]
	v_exp_f32_e32 v40, v40
	v_exp_f32_e32 v41, v41
	s_nop 0
	v_pk_add_f32 v[40:41], v[40:41], 1.0 op_sel_hi:[1,0]
	v_rcp_f32_e32 v40, v40
	v_rcp_f32_e32 v41, v41
	s_nop 0
	v_pk_mul_f32 v[34:35], v[34:35], v[40:41]
	v_pk_mul_f32 v[40:41], v[36:37], v[34:35]
	v_cvt_pk_bf16_f32 v34, v42, v43
	v_cvt_pk_bf16_f32 v35, v44, v45
	v_cvt_pk_bf16_f32 v36, v38, v39
	v_cvt_pk_bf16_f32 v37, v40, v41
	global_store_dwordx4 v[50:51], v[34:37], off sc1
	ds_read2_b32 v[36:37], v155 offset0:160 offset1:176
	s_waitcnt lgkmcnt(0)
	v_pk_mul_f32 v[30:31], v[30:31], v[36:37] op_sel_hi:[1,0]
	v_pk_mul_f32 v[38:39], v[30:31], s[96:97] op_sel_hi:[1,0]
	v_exp_f32_e32 v38, v38
	v_exp_f32_e32 v39, v39
	v_pk_mul_f32 v[26:27], v[26:27], v[36:37] op_sel_hi:[1,0]
	v_pk_mul_f32 v[28:29], v[28:29], v[36:37] op_sel_hi:[1,0]
	v_pk_add_f32 v[38:39], v[38:39], 1.0 op_sel_hi:[1,0]
	v_rcp_f32_e32 v38, v38
	v_rcp_f32_e32 v39, v39
	v_pk_mul_f32 v[22:23], v[22:23], v[36:37] op_sel_hi:[1,0]
	v_pk_mul_f32 v[18:19], v[18:19], v[36:37] op_sel_hi:[1,0]
	v_add_u32_e32 v34, 0xa0, v154
	v_pk_mul_f32 v[30:31], v[30:31], v[38:39]
	v_pk_mul_f32 v[20:21], v[20:21], v[36:37] op_sel_hi:[1,0]
	v_pk_mul_f32 v[26:27], v[26:27], v[30:31]
	v_pk_mul_f32 v[30:31], v[32:33], v[36:37] op_sel_hi:[1,0]
	v_mad_i64_i32 v[34:35], s[6:7], v34, s86, v[142:143]
	v_pk_mul_f32 v[32:33], v[30:31], s[96:97] op_sel_hi:[1,0]
	v_exp_f32_e32 v32, v32
	v_exp_f32_e32 v33, v33
	v_lshl_add_u64 v[34:35], v[34:35], 0, v[144:145]
	v_pk_add_f32 v[32:33], v[32:33], 1.0 op_sel_hi:[1,0]
	v_rcp_f32_e32 v32, v32
	v_rcp_f32_e32 v33, v33
	s_nop 0
	v_pk_mul_f32 v[30:31], v[30:31], v[32:33]
	v_pk_mul_f32 v[28:29], v[28:29], v[30:31]
	v_pk_mul_f32 v[30:31], v[22:23], s[96:97] op_sel_hi:[1,0]
	v_exp_f32_e32 v30, v30
	v_exp_f32_e32 v31, v31
	s_nop 0
	v_pk_add_f32 v[30:31], v[30:31], 1.0 op_sel_hi:[1,0]
	v_rcp_f32_e32 v30, v30
	v_rcp_f32_e32 v31, v31
	s_nop 0
	v_pk_mul_f32 v[22:23], v[22:23], v[30:31]
	v_pk_mul_f32 v[22:23], v[18:19], v[22:23]
	v_pk_mul_f32 v[18:19], v[24:25], v[36:37] op_sel_hi:[1,0]
	v_pk_mul_f32 v[24:25], v[18:19], s[96:97] op_sel_hi:[1,0]
	v_exp_f32_e32 v24, v24
	v_exp_f32_e32 v25, v25
	s_nop 0
	v_pk_add_f32 v[24:25], v[24:25], 1.0 op_sel_hi:[1,0]
	v_rcp_f32_e32 v24, v24
	v_rcp_f32_e32 v25, v25
	s_nop 0
	v_pk_mul_f32 v[18:19], v[18:19], v[24:25]
	v_pk_mul_f32 v[24:25], v[20:21], v[18:19]
	v_cvt_pk_bf16_f32 v18, v26, v27
	v_cvt_pk_bf16_f32 v19, v28, v29
	v_cvt_pk_bf16_f32 v20, v22, v23
	v_cvt_pk_bf16_f32 v21, v24, v25
	global_store_dwordx4 v[34:35], v[18:21], off sc1
	s_nop 1
	v_mov_b32_e32 v20, v37
	v_pk_mul_f32 v[14:15], v[14:15], v[20:21] op_sel_hi:[1,0]
	v_add_u32_e32 v18, 0xb0, v154
	v_mul_f32_e32 v21, 0xbfb8aa3b, v14
	v_exp_f32_e32 v21, v21
	v_mad_i64_i32 v[18:19], s[6:7], v18, s86, v[142:143]
	v_lshl_add_u64 v[18:19], v[18:19], 0, v[144:145]
	v_add_f32_e32 v21, 1.0, v21
	v_rcp_f32_e32 v22, v21
	v_pk_mul_f32 v[10:11], v[10:11], v[20:21] op_sel_hi:[1,0]
	v_mul_f32_e32 v21, 0xbfb8aa3b, v15
	v_exp_f32_e32 v21, v21
	s_nop 0
	v_add_f32_e32 v21, 1.0, v21
	v_rcp_f32_e32 v23, v21
	v_pk_mul_f32 v[12:13], v[12:13], v[20:21] op_sel_hi:[1,0]
	v_pk_mul_f32 v[6:7], v[6:7], v[20:21] op_sel_hi:[1,0]
	v_pk_mul_f32 v[2:3], v[2:3], v[20:21] op_sel_hi:[1,0]
	v_pk_mul_f32 v[14:15], v[14:15], v[22:23]
	v_pk_mul_f32 v[4:5], v[4:5], v[20:21] op_sel_hi:[1,0]
	v_pk_mul_f32 v[10:11], v[10:11], v[14:15]
	v_pk_mul_f32 v[14:15], v[16:17], v[20:21] op_sel_hi:[1,0]
	v_pk_mul_f32 v[16:17], v[14:15], s[96:97] op_sel_hi:[1,0]
	v_exp_f32_e32 v16, v16
	v_exp_f32_e32 v17, v17
	s_nop 0
	v_pk_add_f32 v[16:17], v[16:17], 1.0 op_sel_hi:[1,0]
	v_rcp_f32_e32 v16, v16
	v_rcp_f32_e32 v17, v17
	s_nop 0
	v_pk_mul_f32 v[14:15], v[14:15], v[16:17]
	v_pk_mul_f32 v[12:13], v[12:13], v[14:15]
	v_pk_mul_f32 v[14:15], v[6:7], s[96:97] op_sel_hi:[1,0]
	v_exp_f32_e32 v14, v14
	v_exp_f32_e32 v15, v15
	s_nop 0
	v_pk_add_f32 v[14:15], v[14:15], 1.0 op_sel_hi:[1,0]
	v_rcp_f32_e32 v14, v14
	v_rcp_f32_e32 v15, v15
	s_nop 0
	v_pk_mul_f32 v[6:7], v[6:7], v[14:15]
	v_pk_mul_f32 v[6:7], v[2:3], v[6:7]
	v_pk_mul_f32 v[2:3], v[8:9], v[20:21] op_sel_hi:[1,0]
	v_pk_mul_f32 v[8:9], v[2:3], s[96:97] op_sel_hi:[1,0]
	v_exp_f32_e32 v8, v8
	v_exp_f32_e32 v9, v9
	s_nop 0
	v_pk_add_f32 v[8:9], v[8:9], 1.0 op_sel_hi:[1,0]
	v_rcp_f32_e32 v8, v8
	v_rcp_f32_e32 v9, v9
	s_nop 0
	v_pk_mul_f32 v[2:3], v[2:3], v[8:9]
	v_pk_mul_f32 v[8:9], v[4:5], v[2:3]
	v_cvt_pk_bf16_f32 v2, v10, v11
	v_cvt_pk_bf16_f32 v3, v12, v13
	v_cvt_pk_bf16_f32 v4, v6, v7
	v_cvt_pk_bf16_f32 v5, v8, v9
	global_store_dwordx4 v[18:19], v[2:5], off sc1
	s_cbranch_vccnz .LBB0_46
	s_andn2_b64 vcc, exec, s[44:45]
	s_cbranch_vccnz .LBB0_45
	s_barrier
	s_branch .LBB0_45

.LBB0_78:
	v_lshl_or_b32 v98, s34, 8, v230
	v_lshl_add_u32 v214, s95, 8, v228
	v_ashrrev_i32_e32 v99, 31, v98
	v_lshlrev_b64 v[204:205], 1, v[98:99]
	v_ashrrev_i32_e32 v215, 31, v214
	v_lshl_add_u64 v[98:99], s[36:37], 0, v[204:205]
	v_lshlrev_b64 v[240:241], 11, v[214:215]
	v_lshl_add_u64 v[100:101], v[98:99], 0, v[240:241]
	v_add_co_u32_e32 v102, vcc, 0x4000, v100
	v_or_b32_e32 v212, 16, v214
	s_nop 0
	v_addc_co_u32_e32 v103, vcc, 0, v101, vcc
	global_load_dwordx4 v[244:247], v[100:101], off
	global_load_dwordx4 v[220:223], v[102:103], off
	v_ashrrev_i32_e32 v213, 31, v212
	v_lshlrev_b64 v[226:227], 11, v[212:213]
	v_lshl_add_u64 v[100:101], v[98:99], 0, v[226:227]
	v_add_co_u32_e32 v102, vcc, 0x4000, v100
	v_or_b32_e32 v210, 32, v214
	s_nop 0
	v_addc_co_u32_e32 v103, vcc, 0, v101, vcc
	global_load_dwordx4 v[184:187], v[100:101], off
	global_load_dwordx4 v[180:183], v[102:103], off
	v_ashrrev_i32_e32 v211, 31, v210
	v_lshlrev_b64 v[218:219], 11, v[210:211]
	v_lshl_add_u64 v[100:101], v[98:99], 0, v[218:219]
	v_add_co_u32_e32 v102, vcc, 0x4000, v100
	v_cndmask_b32_e64 v234, v136, v152, s[42:43]
	s_nop 0
	v_addc_co_u32_e32 v103, vcc, 0, v101, vcc
	global_load_dwordx4 v[176:179], v[100:101], off
	global_load_dwordx4 v[172:175], v[102:103], off
	v_mov_b32_e32 v243, v131
	v_or_b32_e32 v208, 48, v214
	v_ashrrev_i32_e32 v209, 31, v208
	v_mov_b32_dpp v243, v234 row_ror:8 row_mask:0xf bank_mask:0xf
	v_cndmask_b32_e64 v152, v152, v243, s[42:43]
	v_cndmask_b32_e64 v136, v243, v136, s[42:43]
	v_cndmask_b32_e64 v234, v137, v153, s[42:43]
	v_mov_b32_e32 v243, v131
	v_lshlrev_b64 v[216:217], 11, v[208:209]
	v_lshl_add_u64 v[100:101], v[98:99], 0, v[216:217]
	v_mov_b32_dpp v243, v234 row_ror:8 row_mask:0xf bank_mask:0xf
	v_cndmask_b32_e64 v153, v153, v243, s[42:43]
	v_cndmask_b32_e64 v137, v243, v137, s[42:43]
	v_cndmask_b32_e64 v234, v138, v154, s[42:43]
	v_mov_b32_e32 v243, v131
	v_add_u32_e32 v206, 0x80, v214
	v_add_co_u32_e32 v102, vcc, 0x4000, v100
	v_mov_b32_dpp v243, v234 row_ror:8 row_mask:0xf bank_mask:0xf
	v_cndmask_b32_e64 v154, v154, v243, s[42:43]
	v_cndmask_b32_e64 v138, v243, v138, s[42:43]
	v_cndmask_b32_e64 v234, v139, v155, s[42:43]
	v_mov_b32_e32 v243, v131
	v_ashrrev_i32_e32 v207, 31, v206
	v_addc_co_u32_e32 v103, vcc, 0, v101, vcc
	v_mov_b32_dpp v243, v234 row_ror:8 row_mask:0xf bank_mask:0xf
	v_cndmask_b32_e64 v155, v155, v243, s[42:43]
	v_cndmask_b32_e64 v139, v243, v139, s[42:43]
	v_cndmask_b32_e64 v234, v132, v140, s[42:43]
	v_mov_b32_e32 v243, v131
	global_load_dwordx4 v[168:171], v[100:101], off
	global_load_dwordx4 v[164:167], v[102:103], off
	v_mov_b32_dpp v243, v234 row_ror:8 row_mask:0xf bank_mask:0xf
	v_cndmask_b32_e64 v140, v140, v243, s[42:43]
	v_cndmask_b32_e64 v234, v243, v132, s[42:43]
	v_cndmask_b32_e64 v132, v133, v141, s[42:43]
	v_mov_b32_e32 v243, v131
	v_lshlrev_b64 v[100:101], 11, v[206:207]
	v_lshl_add_u64 v[100:101], v[98:99], 0, v[100:101]
	v_mov_b32_dpp v243, v132 row_ror:8 row_mask:0xf bank_mask:0xf
	v_cndmask_b32_e64 v141, v141, v243, s[42:43]
	v_cndmask_b32_e64 v243, v243, v133, s[42:43]
	v_cndmask_b32_e64 v132, v134, v142, s[42:43]
	v_mov_b32_e32 v133, v131
	v_add_u32_e32 v202, 0x90, v214
	v_add_co_u32_e32 v102, vcc, 0x4000, v100
	v_mov_b32_dpp v133, v132 row_ror:8 row_mask:0xf bank_mask:0xf
	v_ashrrev_i32_e32 v203, 31, v202
	v_cndmask_b32_e64 v142, v142, v133, s[42:43]
	v_cndmask_b32_e64 v237, v133, v134, s[42:43]
	v_cndmask_b32_e64 v132, v135, v143, s[42:43]
	v_mov_b32_e32 v133, v131
	v_addc_co_u32_e32 v103, vcc, 0, v101, vcc
	global_load_dwordx4 v[160:163], v[100:101], off
	global_load_dwordx4 v[156:159], v[102:103], off
	v_lshlrev_b64 v[100:101], 11, v[202:203]
	v_mov_b32_dpp v133, v132 row_ror:8 row_mask:0xf bank_mask:0xf
	v_lshl_add_u64 v[100:101], v[98:99], 0, v[100:101]
	v_add_u32_e32 v200, 0xa0, v214
	v_cndmask_b32_e64 v143, v143, v133, s[42:43]
	v_cndmask_b32_e64 v135, v133, v135, s[42:43]
	s_waitcnt vmcnt(0)
	v_lshlrev_b32_e32 v133, 16, v245
	v_add_co_u32_e32 v102, vcc, 0x4000, v100
	v_ashrrev_i32_e32 v201, 31, v200
	v_add_f32_e32 v154, v154, v133
	v_and_b32_e32 v133, 0xffff0000, v245
	v_addc_co_u32_e32 v103, vcc, 0, v101, vcc
	global_load_dwordx4 v[148:151], v[100:101], off
	global_load_dwordx4 v[144:147], v[102:103], off
	v_lshlrev_b64 v[100:101], 11, v[200:201]
	v_add_f32_e32 v155, v155, v133
	v_lshlrev_b32_e32 v133, 16, v221
	v_lshl_add_u64 v[100:101], v[98:99], 0, v[100:101]
	v_add_u32_e32 v198, 0xb0, v214
	v_add_f32_e32 v245, v138, v133
	v_and_b32_e32 v133, 0xffff0000, v221
	v_add_co_u32_e32 v102, vcc, 0x4000, v100
	v_ashrrev_i32_e32 v199, 31, v198
	v_lshlrev_b32_e32 v132, 16, v244
	v_add_f32_e32 v221, v139, v133
	v_lshlrev_b32_e32 v134, 16, v246
	v_lshlrev_b32_e32 v139, 16, v247
	v_addc_co_u32_e32 v103, vcc, 0, v101, vcc
	global_load_dwordx4 v[126:129], v[100:101], off
	global_load_dwordx4 v[122:125], v[102:103], off
	v_lshlrev_b64 v[100:101], 11, v[198:199]
	v_add_f32_e32 v152, v152, v132
	v_and_b32_e32 v132, 0xffff0000, v244
	v_add_f32_e32 v229, v140, v134
	v_and_b32_e32 v134, 0xffff0000, v246
	v_add_f32_e32 v142, v142, v139
	v_and_b32_e32 v139, 0xffff0000, v247
	v_lshl_add_u64 v[98:99], v[98:99], 0, v[100:101]
	v_add_f32_e32 v153, v153, v132
	v_lshlrev_b32_e32 v132, 16, v220
	v_add_f32_e32 v246, v141, v134
	v_lshlrev_b32_e32 v134, 16, v222
	v_add_f32_e32 v143, v143, v139
	v_lshlrev_b32_e32 v139, 16, v223
	v_add_co_u32_e32 v100, vcc, 0x4000, v98
	v_add_f32_e32 v244, v136, v132
	v_and_b32_e32 v132, 0xffff0000, v220
	v_add_f32_e32 v234, v234, v134
	v_and_b32_e32 v134, 0xffff0000, v222
	v_add_f32_e32 v237, v237, v139
	v_and_b32_e32 v139, 0xffff0000, v223
	v_lshl_add_u64 v[140:141], s[36:37], 0, v[240:241]
	v_addc_co_u32_e32 v101, vcc, 0, v99, vcc
	v_add_f32_e32 v220, v137, v132
	v_cvt_pk_bf16_f32 v132, v152, v153
	v_cvt_pk_bf16_f32 v133, v154, v155
	v_add_f32_e32 v222, v243, v134
	v_cvt_pk_bf16_f32 v134, v229, v246
	v_add_f32_e32 v223, v135, v139
	v_cvt_pk_bf16_f32 v135, v142, v143
	v_lshl_add_u64 v[140:141], v[140:141], 0, v[204:205]
	global_load_dwordx4 v[102:105], v[98:99], off
	s_nop 0
	global_load_dwordx4 v[98:101], v[100:101], off
	global_store_dwordx4 v[140:141], v[132:135], off sc1
	v_cvt_pk_bf16_f32 v136, v244, v220
	v_cvt_pk_bf16_f32 v137, v245, v221
	v_add_co_u32_e32 v132, vcc, s97, v140
	v_cvt_pk_bf16_f32 v138, v234, v222
	v_cvt_pk_bf16_f32 v139, v237, v223
	v_addc_co_u32_e32 v133, vcc, 0, v141, vcc
	global_store_dwordx4 v[132:133], v[136:139], off sc1
	v_cndmask_b32_e64 v132, v110, v118, s[42:43]
	v_mov_b32_e32 v133, v131
	s_lshl_b32 s60, s34, 2
	s_ashr_i32 s61, s60, 31
	v_mov_b32_dpp v133, v132 row_ror:8 row_mask:0xf bank_mask:0xf
	v_cndmask_b32_e64 v118, v118, v133, s[42:43]
	v_cndmask_b32_e64 v110, v133, v110, s[42:43]
	v_cndmask_b32_e64 v132, v111, v119, s[42:43]
	v_mov_b32_e32 v133, v131
	s_nop 1
	v_mov_b32_dpp v133, v132 row_ror:8 row_mask:0xf bank_mask:0xf
	v_cndmask_b32_e64 v119, v119, v133, s[42:43]
	v_cndmask_b32_e64 v111, v133, v111, s[42:43]
	v_cndmask_b32_e64 v132, v112, v120, s[42:43]
	v_mov_b32_e32 v133, v131
	s_nop 1
	v_mov_b32_dpp v133, v132 row_ror:8 row_mask:0xf bank_mask:0xf
	v_cndmask_b32_e64 v120, v120, v133, s[42:43]
	v_cndmask_b32_e64 v112, v133, v112, s[42:43]
	v_cndmask_b32_e64 v132, v113, v121, s[42:43]
	v_mov_b32_e32 v133, v131
	s_nop 1
	v_mov_b32_dpp v133, v132 row_ror:8 row_mask:0xf bank_mask:0xf
	v_cndmask_b32_e64 v121, v121, v133, s[42:43]
	v_cndmask_b32_e64 v113, v133, v113, s[42:43]
	v_cndmask_b32_e64 v132, v106, v114, s[42:43]
	v_mov_b32_e32 v133, v131
	s_nop 1
	v_mov_b32_dpp v133, v132 row_ror:8 row_mask:0xf bank_mask:0xf
	v_cndmask_b32_e64 v134, v114, v133, s[42:43]
	v_cndmask_b32_e64 v135, v133, v106, s[42:43]
	v_cndmask_b32_e64 v106, v107, v115, s[42:43]
	v_mov_b32_e32 v114, v131
	s_nop 1
	v_mov_b32_dpp v114, v106 row_ror:8 row_mask:0xf bank_mask:0xf
	v_cndmask_b32_e64 v139, v114, v107, s[42:43]
	v_cndmask_b32_e64 v106, v108, v116, s[42:43]
	v_mov_b32_e32 v107, v131
	v_cndmask_b32_e64 v138, v115, v114, s[42:43]
	s_nop 0
	v_mov_b32_dpp v107, v106 row_ror:8 row_mask:0xf bank_mask:0xf
	v_cndmask_b32_e64 v116, v116, v107, s[42:43]
	v_cndmask_b32_e64 v140, v107, v108, s[42:43]
	v_cndmask_b32_e64 v106, v109, v117, s[42:43]
	v_mov_b32_e32 v107, v131
	s_nop 1
	v_mov_b32_dpp v107, v106 row_ror:8 row_mask:0xf bank_mask:0xf
	v_cndmask_b32_e64 v117, v117, v107, s[42:43]
	v_cndmask_b32_e64 v141, v107, v109, s[42:43]
	v_and_b32_e32 v107, 0xffff0000, v184
	v_add_f32_e32 v108, v119, v107
	v_lshlrev_b32_e32 v107, 16, v180
	v_and_b32_e32 v109, 0xffff0000, v180
	v_add_f32_e32 v107, v110, v107
	v_add_f32_e32 v111, v111, v109
	v_lshlrev_b32_e32 v109, 16, v185
	v_and_b32_e32 v110, 0xffff0000, v185
	v_add_f32_e32 v109, v120, v109
	v_add_f32_e32 v114, v121, v110
	v_lshlrev_b32_e32 v110, 16, v181
	v_lshlrev_b32_e32 v120, 16, v187
	v_add_f32_e32 v110, v112, v110
	v_and_b32_e32 v112, 0xffff0000, v181
	v_add_f32_e32 v116, v116, v120
	v_and_b32_e32 v120, 0xffff0000, v187
	v_lshlrev_b32_e32 v106, 16, v184
	v_add_f32_e32 v115, v113, v112
	v_lshlrev_b32_e32 v112, 16, v186
	v_and_b32_e32 v113, 0xffff0000, v186
	v_add_f32_e32 v120, v117, v120
	v_lshlrev_b32_e32 v117, 16, v183
	v_and_b32_e32 v121, 0xffff0000, v183
	v_add_f32_e32 v106, v118, v106
	v_add_f32_e32 v112, v134, v112
	v_add_f32_e32 v118, v138, v113
	v_lshlrev_b32_e32 v113, 16, v182
	v_add_f32_e32 v117, v140, v117
	v_add_f32_e32 v121, v141, v121
	v_lshl_add_u64 v[140:141], s[36:37], 0, v[226:227]
	v_cvt_pk_bf16_f32 v132, v106, v108
	v_cvt_pk_bf16_f32 v133, v109, v114
	v_add_f32_e32 v113, v135, v113
	v_and_b32_e32 v119, 0xffff0000, v182
	v_cvt_pk_bf16_f32 v134, v112, v118
	v_cvt_pk_bf16_f32 v135, v116, v120
	v_lshl_add_u64 v[140:141], v[140:141], 0, v[204:205]
	v_add_f32_e32 v119, v139, v119
	global_store_dwordx4 v[140:141], v[132:135], off sc1
	v_cvt_pk_bf16_f32 v136, v107, v111
	v_cvt_pk_bf16_f32 v137, v110, v115
	v_add_co_u32_e32 v132, vcc, s97, v140
	v_cvt_pk_bf16_f32 v138, v113, v119
	v_cvt_pk_bf16_f32 v139, v117, v121
	v_addc_co_u32_e32 v133, vcc, 0, v141, vcc
	global_store_dwordx4 v[132:133], v[136:139], off sc1
	v_cndmask_b32_e64 v132, v86, v94, s[42:43]
	v_mov_b32_e32 v133, v131
	s_nop 1
	v_mov_b32_dpp v133, v132 row_ror:8 row_mask:0xf bank_mask:0xf
	v_cndmask_b32_e64 v94, v94, v133, s[42:43]
	v_cndmask_b32_e64 v86, v133, v86, s[42:43]
	v_cndmask_b32_e64 v132, v87, v95, s[42:43]
	v_mov_b32_e32 v133, v131
	s_nop 1
	v_mov_b32_dpp v133, v132 row_ror:8 row_mask:0xf bank_mask:0xf
	v_cndmask_b32_e64 v95, v95, v133, s[42:43]
	v_cndmask_b32_e64 v87, v133, v87, s[42:43]
	v_cndmask_b32_e64 v132, v88, v96, s[42:43]
	v_mov_b32_e32 v133, v131
	s_nop 1
	v_mov_b32_dpp v133, v132 row_ror:8 row_mask:0xf bank_mask:0xf
	v_cndmask_b32_e64 v96, v96, v133, s[42:43]
	v_cndmask_b32_e64 v88, v133, v88, s[42:43]
	v_cndmask_b32_e64 v132, v89, v97, s[42:43]
	v_mov_b32_e32 v133, v131
	s_nop 1
	v_mov_b32_dpp v133, v132 row_ror:8 row_mask:0xf bank_mask:0xf
	v_cndmask_b32_e64 v97, v97, v133, s[42:43]
	v_cndmask_b32_e64 v89, v133, v89, s[42:43]
	v_cndmask_b32_e64 v132, v82, v90, s[42:43]
	v_mov_b32_e32 v133, v131
	s_nop 1
	v_mov_b32_dpp v133, v132 row_ror:8 row_mask:0xf bank_mask:0xf
	v_cndmask_b32_e64 v134, v90, v133, s[42:43]
	v_cndmask_b32_e64 v135, v133, v82, s[42:43]
	v_cndmask_b32_e64 v82, v83, v91, s[42:43]
	v_mov_b32_e32 v90, v131
	s_nop 1
	v_mov_b32_dpp v90, v82 row_ror:8 row_mask:0xf bank_mask:0xf
	v_cndmask_b32_e64 v139, v90, v83, s[42:43]
	v_cndmask_b32_e64 v82, v84, v92, s[42:43]
	v_mov_b32_e32 v83, v131
	v_cndmask_b32_e64 v138, v91, v90, s[42:43]
	s_nop 0
	v_mov_b32_dpp v83, v82 row_ror:8 row_mask:0xf bank_mask:0xf
	v_cndmask_b32_e64 v92, v92, v83, s[42:43]
	v_cndmask_b32_e64 v140, v83, v84, s[42:43]
	v_cndmask_b32_e64 v82, v85, v93, s[42:43]
	v_mov_b32_e32 v83, v131
	s_nop 1
	v_mov_b32_dpp v83, v82 row_ror:8 row_mask:0xf bank_mask:0xf
	v_cndmask_b32_e64 v93, v93, v83, s[42:43]
	v_cndmask_b32_e64 v141, v83, v85, s[42:43]
	v_and_b32_e32 v83, 0xffff0000, v176
	v_add_f32_e32 v84, v95, v83
	v_lshlrev_b32_e32 v83, 16, v172
	v_and_b32_e32 v85, 0xffff0000, v172
	v_add_f32_e32 v83, v86, v83
	v_add_f32_e32 v87, v87, v85
	v_lshlrev_b32_e32 v85, 16, v177
	v_and_b32_e32 v86, 0xffff0000, v177
	v_add_f32_e32 v85, v96, v85
	v_add_f32_e32 v90, v97, v86
	v_lshlrev_b32_e32 v86, 16, v173
	v_lshlrev_b32_e32 v96, 16, v179
	v_add_f32_e32 v86, v88, v86
	v_and_b32_e32 v88, 0xffff0000, v173
	v_add_f32_e32 v92, v92, v96
	v_and_b32_e32 v96, 0xffff0000, v179
	v_lshlrev_b32_e32 v82, 16, v176
	v_add_f32_e32 v91, v89, v88
	v_lshlrev_b32_e32 v88, 16, v178
	v_and_b32_e32 v89, 0xffff0000, v178
	v_add_f32_e32 v96, v93, v96
	v_lshlrev_b32_e32 v93, 16, v175
	v_and_b32_e32 v97, 0xffff0000, v175
	v_add_f32_e32 v82, v94, v82
	v_add_f32_e32 v88, v134, v88
	v_add_f32_e32 v94, v138, v89
	v_lshlrev_b32_e32 v89, 16, v174
	v_add_f32_e32 v93, v140, v93
	v_add_f32_e32 v97, v141, v97
	v_lshl_add_u64 v[140:141], s[36:37], 0, v[218:219]
	v_cvt_pk_bf16_f32 v132, v82, v84
	v_cvt_pk_bf16_f32 v133, v85, v90
	v_add_f32_e32 v89, v135, v89
	v_and_b32_e32 v95, 0xffff0000, v174
	v_cvt_pk_bf16_f32 v134, v88, v94
	v_cvt_pk_bf16_f32 v135, v92, v96
	v_lshl_add_u64 v[140:141], v[140:141], 0, v[204:205]
	v_add_f32_e32 v95, v139, v95
	global_store_dwordx4 v[140:141], v[132:135], off sc1
	v_cvt_pk_bf16_f32 v136, v83, v87
	v_cvt_pk_bf16_f32 v137, v86, v91
	v_add_co_u32_e32 v132, vcc, s97, v140
	v_cvt_pk_bf16_f32 v138, v89, v95
	v_cvt_pk_bf16_f32 v139, v93, v97
	v_addc_co_u32_e32 v133, vcc, 0, v141, vcc
	global_store_dwordx4 v[132:133], v[136:139], off sc1
	v_cndmask_b32_e64 v132, v70, v78, s[42:43]
	v_mov_b32_e32 v133, v131
	s_nop 1
	v_mov_b32_dpp v133, v132 row_ror:8 row_mask:0xf bank_mask:0xf
	v_cndmask_b32_e64 v78, v78, v133, s[42:43]
	v_cndmask_b32_e64 v70, v133, v70, s[42:43]
	v_cndmask_b32_e64 v132, v71, v79, s[42:43]
	v_mov_b32_e32 v133, v131
	s_nop 1
	v_mov_b32_dpp v133, v132 row_ror:8 row_mask:0xf bank_mask:0xf
	v_cndmask_b32_e64 v79, v79, v133, s[42:43]
	v_cndmask_b32_e64 v71, v133, v71, s[42:43]
	v_cndmask_b32_e64 v132, v72, v80, s[42:43]
	v_mov_b32_e32 v133, v131
	s_nop 1
	v_mov_b32_dpp v133, v132 row_ror:8 row_mask:0xf bank_mask:0xf
	v_cndmask_b32_e64 v80, v80, v133, s[42:43]
	v_cndmask_b32_e64 v72, v133, v72, s[42:43]
	v_cndmask_b32_e64 v132, v73, v81, s[42:43]
	v_mov_b32_e32 v133, v131
	s_nop 1
	v_mov_b32_dpp v133, v132 row_ror:8 row_mask:0xf bank_mask:0xf
	v_cndmask_b32_e64 v81, v81, v133, s[42:43]
	v_cndmask_b32_e64 v132, v133, v73, s[42:43]
	v_cndmask_b32_e64 v73, v66, v74, s[42:43]
	v_mov_b32_e32 v133, v131
	s_nop 1
	v_mov_b32_dpp v133, v73 row_ror:8 row_mask:0xf bank_mask:0xf
	v_cndmask_b32_e64 v74, v74, v133, s[42:43]
	v_cndmask_b32_e64 v133, v133, v66, s[42:43]
	v_cndmask_b32_e64 v66, v67, v75, s[42:43]
	v_mov_b32_e32 v73, v131
	s_nop 1
	v_mov_b32_dpp v73, v66 row_ror:8 row_mask:0xf bank_mask:0xf
	v_cndmask_b32_e64 v136, v73, v67, s[42:43]
	v_cndmask_b32_e64 v66, v68, v76, s[42:43]
	v_mov_b32_e32 v67, v131
	v_cndmask_b32_e64 v75, v75, v73, s[42:43]
	s_nop 0
	v_mov_b32_dpp v67, v66 row_ror:8 row_mask:0xf bank_mask:0xf
	v_cndmask_b32_e64 v137, v76, v67, s[42:43]
	v_cndmask_b32_e64 v141, v67, v68, s[42:43]
	v_cndmask_b32_e64 v66, v69, v77, s[42:43]
	v_mov_b32_e32 v67, v131
	s_nop 1
	v_mov_b32_dpp v67, v66 row_ror:8 row_mask:0xf bank_mask:0xf
	v_cndmask_b32_e64 v172, v77, v67, s[42:43]
	v_cndmask_b32_e64 v173, v67, v69, s[42:43]
	v_and_b32_e32 v67, 0xffff0000, v168
	v_add_f32_e32 v68, v79, v67
	v_lshlrev_b32_e32 v67, 16, v164
	v_add_f32_e32 v67, v70, v67
	v_and_b32_e32 v70, 0xffff0000, v169
	v_add_f32_e32 v76, v81, v70
	v_lshlrev_b32_e32 v70, 16, v165
	v_add_f32_e32 v72, v72, v70
	v_and_b32_e32 v70, 0xffff0000, v165
	v_and_b32_e32 v69, 0xffff0000, v164
	v_add_f32_e32 v77, v132, v70
	v_lshlrev_b32_e32 v70, 16, v170
	v_add_f32_e32 v73, v71, v69
	v_lshlrev_b32_e32 v69, 16, v169
	v_add_f32_e32 v74, v74, v70
	v_and_b32_e32 v70, 0xffff0000, v170
	v_add_f32_e32 v69, v80, v69
	v_add_f32_e32 v80, v75, v70
	v_lshlrev_b32_e32 v70, 16, v166
	v_add_f32_e32 v75, v133, v70
	v_and_b32_e32 v70, 0xffff0000, v166
	v_lshlrev_b32_e32 v66, 16, v168
	v_add_f32_e32 v81, v136, v70
	v_lshlrev_b32_e32 v70, 16, v171
	v_add_f32_e32 v66, v78, v66
	v_add_f32_e32 v78, v137, v70
	v_and_b32_e32 v70, 0xffff0000, v171
	v_add_f32_e32 v132, v172, v70
	v_lshlrev_b32_e32 v70, 16, v167
	v_add_f32_e32 v79, v141, v70
	v_and_b32_e32 v70, 0xffff0000, v167
	v_add_f32_e32 v133, v173, v70
	v_lshl_add_u64 v[70:71], s[36:37], 0, v[216:217]
	v_cvt_pk_bf16_f32 v134, v66, v68
	v_cvt_pk_bf16_f32 v135, v69, v76
	v_cvt_pk_bf16_f32 v136, v74, v80
	v_cvt_pk_bf16_f32 v137, v78, v132
	v_lshl_add_u64 v[70:71], v[70:71], 0, v[204:205]
	global_store_dwordx4 v[70:71], v[134:137], off sc1
	v_add_co_u32_e32 v70, vcc, s97, v70
	v_cvt_pk_bf16_f32 v138, v67, v73
	v_cvt_pk_bf16_f32 v139, v72, v77
	v_cvt_pk_bf16_f32 v140, v75, v81
	v_cvt_pk_bf16_f32 v141, v79, v133
	v_addc_co_u32_e32 v71, vcc, 0, v71, vcc
	global_store_dwordx4 v[70:71], v[138:141], off sc1
	v_mul_f32_e32 v70, v220, v220
	v_mul_f32_e32 v71, v221, v221
	v_fmac_f32_e32 v70, v244, v244
	v_fmac_f32_e32 v71, v245, v245
	v_add_f32_e32 v70, v70, v71
	v_mul_f32_e32 v71, v222, v222
	v_fmac_f32_e32 v71, v234, v234
	v_add_f32_e32 v70, v70, v71
	v_mul_f32_e32 v71, v223, v223
	v_fmac_f32_e32 v71, v237, v237
	v_add_f32_e32 v70, v70, v71
	v_mul_f32_e32 v71, v153, v153
	v_mul_f32_e32 v134, v155, v155
	v_fmac_f32_e32 v71, v152, v152
	v_fmac_f32_e32 v134, v154, v154
	v_add_f32_e32 v71, v71, v134
	v_mul_f32_e32 v134, v246, v246
	v_fmac_f32_e32 v134, v229, v229
	v_add_f32_e32 v71, v71, v134
	v_mul_f32_e32 v134, v143, v143
	v_fmac_f32_e32 v134, v142, v142
	v_add_f32_e32 v71, v71, v134
	v_and_b32_e32 v134, 64, v232
	v_add_u32_e32 v136, 64, v134
	v_add_f32_dpp v135, v70, v70 row_ror:8 row_mask:0xf bank_mask:0xf bound_ctrl:1
	v_xor_b32_e32 v70, 16, v232
	v_cmp_lt_i32_e32 vcc, v70, v136
	v_add_f32_dpp v71, v71, v71 row_ror:8 row_mask:0xf bank_mask:0xf bound_ctrl:1
	s_nop 0
	v_cndmask_b32_e32 v70, v232, v70, vcc
	v_lshlrev_b32_e32 v70, 2, v70
	ds_bpermute_b32 v134, v70, v71
	ds_bpermute_b32 v137, v70, v135
	s_waitcnt lgkmcnt(1)
	v_add_f32_e32 v134, v71, v134
	v_xor_b32_e32 v71, 32, v232
	v_cmp_lt_i32_e32 vcc, v71, v136
	s_waitcnt lgkmcnt(0)
	v_add_f32_e32 v135, v135, v137
	v_cndmask_b32_e32 v71, v232, v71, vcc
	v_lshlrev_b32_e32 v71, 2, v71
	ds_bpermute_b32 v136, v71, v134
	ds_bpermute_b32 v137, v71, v135
	s_and_saveexec_b64 s[28:29], s[56:57]
	s_cbranch_execz .LBB0_80
	s_waitcnt lgkmcnt(0)
	v_add_f32_e32 v137, v135, v137
	v_add_f32_e32 v136, v134, v136
	v_lshlrev_b64 v[134:135], 6, v[214:215]
	v_lshl_add_u64 v[134:135], s[52:53], 0, v[134:135]
	v_lshl_add_u64 v[134:135], s[60:61], 2, v[134:135]
	s_lshl_b32 s34, s72, 2
	v_lshl_add_u64 v[134:135], v[134:135], 0, s[34:35]
	global_store_dword v[134:135], v136, off sc1
	global_store_dword v[134:135], v137, off offset:512 sc1
.LBB0_80:
	s_or_b64 exec, exec, s[28:29]
	v_mul_f32_e32 v108, v108, v108
	v_fmac_f32_e32 v108, v106, v106
	v_mul_f32_e32 v106, v111, v111
	v_fmac_f32_e32 v106, v107, v107
	v_mul_f32_e32 v107, v114, v114
	v_fmac_f32_e32 v107, v109, v109
	v_add_f32_e32 v107, v108, v107
	v_mul_f32_e32 v108, v115, v115
	v_fmac_f32_e32 v108, v110, v110
	v_add_f32_e32 v106, v106, v108
	v_mul_f32_e32 v108, v118, v118
	v_fmac_f32_e32 v108, v112, v112
	v_add_f32_e32 v107, v107, v108
	v_mul_f32_e32 v108, v119, v119
	v_fmac_f32_e32 v108, v113, v113
	v_add_f32_e32 v106, v106, v108
	v_mul_f32_e32 v108, v120, v120
	v_fmac_f32_e32 v108, v116, v116
	v_add_f32_e32 v107, v107, v108
	v_mul_f32_e32 v108, v121, v121
	v_fmac_f32_e32 v108, v117, v117
	v_add_f32_e32 v106, v106, v108
	s_nop 1
	v_add_f32_dpp v107, v107, v107 row_ror:8 row_mask:0xf bank_mask:0xf bound_ctrl:1
	v_add_f32_dpp v108, v106, v106 row_ror:8 row_mask:0xf bank_mask:0xf bound_ctrl:1
	ds_bpermute_b32 v106, v70, v107
	ds_bpermute_b32 v109, v70, v108
	s_waitcnt lgkmcnt(1)
	v_add_f32_e32 v106, v107, v106
	s_waitcnt lgkmcnt(0)
	v_add_f32_e32 v107, v108, v109
	ds_bpermute_b32 v108, v71, v106
	ds_bpermute_b32 v109, v71, v107
	s_and_saveexec_b64 s[28:29], s[56:57]
	s_cbranch_execz .LBB0_82
	s_waitcnt lgkmcnt(0)
	v_add_f32_e32 v109, v107, v109
	v_add_f32_e32 v108, v106, v108
	v_lshlrev_b64 v[106:107], 6, v[212:213]
	v_lshl_add_u64 v[106:107], s[52:53], 0, v[106:107]
	v_lshl_add_u64 v[106:107], s[60:61], 2, v[106:107]
	s_lshl_b32 s34, s72, 2
	v_lshl_add_u64 v[106:107], v[106:107], 0, s[34:35]
	global_store_dword v[106:107], v108, off sc1
	global_store_dword v[106:107], v109, off offset:512 sc1
.LBB0_82:
	s_or_b64 exec, exec, s[28:29]
	v_mul_f32_e32 v84, v84, v84
	v_fmac_f32_e32 v84, v82, v82
	v_mul_f32_e32 v82, v87, v87
	v_fmac_f32_e32 v82, v83, v83
	v_mul_f32_e32 v83, v90, v90
	v_fmac_f32_e32 v83, v85, v85
	v_add_f32_e32 v83, v84, v83
	v_mul_f32_e32 v84, v91, v91
	v_fmac_f32_e32 v84, v86, v86
	v_add_f32_e32 v82, v82, v84
	v_mul_f32_e32 v84, v94, v94
	v_fmac_f32_e32 v84, v88, v88
	v_add_f32_e32 v83, v83, v84
	v_mul_f32_e32 v84, v95, v95
	v_fmac_f32_e32 v84, v89, v89
	v_add_f32_e32 v82, v82, v84
	v_mul_f32_e32 v84, v96, v96
	v_fmac_f32_e32 v84, v92, v92
	v_add_f32_e32 v83, v83, v84
	v_mul_f32_e32 v84, v97, v97
	v_fmac_f32_e32 v84, v93, v93
	v_add_f32_e32 v82, v82, v84
	s_nop 1
	v_add_f32_dpp v83, v83, v83 row_ror:8 row_mask:0xf bank_mask:0xf bound_ctrl:1
	v_add_f32_dpp v84, v82, v82 row_ror:8 row_mask:0xf bank_mask:0xf bound_ctrl:1
	ds_bpermute_b32 v82, v70, v83
	ds_bpermute_b32 v85, v70, v84
	s_waitcnt lgkmcnt(1)
	v_add_f32_e32 v82, v83, v82
	s_waitcnt lgkmcnt(0)
	v_add_f32_e32 v83, v84, v85
	ds_bpermute_b32 v84, v71, v82
	ds_bpermute_b32 v85, v71, v83
	s_and_saveexec_b64 s[28:29], s[56:57]
	s_cbranch_execz .LBB0_84
	s_waitcnt lgkmcnt(0)
	v_add_f32_e32 v85, v83, v85
	v_add_f32_e32 v84, v82, v84
	v_lshlrev_b64 v[82:83], 6, v[210:211]
	v_lshl_add_u64 v[82:83], s[52:53], 0, v[82:83]
	v_lshl_add_u64 v[82:83], s[60:61], 2, v[82:83]
	s_lshl_b32 s34, s72, 2
	v_lshl_add_u64 v[82:83], v[82:83], 0, s[34:35]
	global_store_dword v[82:83], v84, off sc1
	global_store_dword v[82:83], v85, off offset:512 sc1
.LBB0_84:
	s_or_b64 exec, exec, s[28:29]
	v_mul_f32_e32 v68, v68, v68
	v_fmac_f32_e32 v68, v66, v66
	v_mul_f32_e32 v66, v73, v73
	v_fmac_f32_e32 v66, v67, v67
	v_mul_f32_e32 v67, v76, v76
	v_fmac_f32_e32 v67, v69, v69
	v_add_f32_e32 v67, v68, v67
	v_mul_f32_e32 v68, v77, v77
	v_fmac_f32_e32 v68, v72, v72
	v_add_f32_e32 v66, v66, v68
	v_mul_f32_e32 v68, v80, v80
	v_fmac_f32_e32 v68, v74, v74
	v_add_f32_e32 v67, v67, v68
	v_mul_f32_e32 v68, v81, v81
	v_fmac_f32_e32 v68, v75, v75
	v_add_f32_e32 v66, v66, v68
	v_mul_f32_e32 v68, v132, v132
	v_fmac_f32_e32 v68, v78, v78
	v_add_f32_e32 v67, v67, v68
	v_mul_f32_e32 v68, v133, v133
	v_fmac_f32_e32 v68, v79, v79
	v_add_f32_e32 v66, v66, v68
	s_nop 1
	v_add_f32_dpp v67, v67, v67 row_ror:8 row_mask:0xf bank_mask:0xf bound_ctrl:1
	v_add_f32_dpp v68, v66, v66 row_ror:8 row_mask:0xf bank_mask:0xf bound_ctrl:1
	ds_bpermute_b32 v66, v70, v67
	ds_bpermute_b32 v69, v70, v68
	s_waitcnt lgkmcnt(1)
	v_add_f32_e32 v66, v67, v66
	s_waitcnt lgkmcnt(0)
	v_add_f32_e32 v67, v68, v69
	ds_bpermute_b32 v68, v71, v66
	ds_bpermute_b32 v69, v71, v67
	s_and_saveexec_b64 s[28:29], s[56:57]
	s_cbranch_execz .LBB0_86
	s_waitcnt lgkmcnt(0)
	v_add_f32_e32 v69, v67, v69
	v_add_f32_e32 v68, v66, v68
	v_lshlrev_b64 v[66:67], 6, v[208:209]
	v_lshl_add_u64 v[66:67], s[52:53], 0, v[66:67]
	v_lshl_add_u64 v[66:67], s[60:61], 2, v[66:67]
	s_lshl_b32 s34, s72, 2
	v_lshl_add_u64 v[66:67], v[66:67], 0, s[34:35]
	global_store_dword v[66:67], v68, off sc1
	global_store_dword v[66:67], v69, off offset:512 sc1
.LBB0_86:
	s_or_b64 exec, exec, s[28:29]
	v_cndmask_b32_e64 v76, v54, v62, s[42:43]
	v_mov_b32_e32 v77, v131
	v_lshlrev_b64 v[72:73], 10, v[206:207]
	v_lshlrev_b64 v[74:75], 10, v[202:203]
	v_mov_b32_dpp v77, v76 row_ror:8 row_mask:0xf bank_mask:0xf
	v_cndmask_b32_e64 v62, v62, v77, s[42:43]
	v_cndmask_b32_e64 v54, v77, v54, s[42:43]
	v_cndmask_b32_e64 v76, v55, v63, s[42:43]
	v_mov_b32_e32 v77, v131
	s_waitcnt lgkmcnt(0)
	v_lshlrev_b64 v[68:69], 10, v[200:201]
	v_lshlrev_b64 v[66:67], 10, v[198:199]
	v_mov_b32_dpp v77, v76 row_ror:8 row_mask:0xf bank_mask:0xf
	v_cndmask_b32_e64 v63, v63, v77, s[42:43]
	v_cndmask_b32_e64 v55, v77, v55, s[42:43]
	v_cndmask_b32_e64 v76, v56, v64, s[42:43]
	v_mov_b32_e32 v77, v131
	s_nop 1
	v_mov_b32_dpp v77, v76 row_ror:8 row_mask:0xf bank_mask:0xf
	v_cndmask_b32_e64 v64, v64, v77, s[42:43]
	v_cndmask_b32_e64 v56, v77, v56, s[42:43]
	v_cndmask_b32_e64 v76, v57, v65, s[42:43]
	v_mov_b32_e32 v77, v131
	s_nop 1
	v_mov_b32_dpp v77, v76 row_ror:8 row_mask:0xf bank_mask:0xf
	v_cndmask_b32_e64 v65, v65, v77, s[42:43]
	v_cndmask_b32_e64 v57, v77, v57, s[42:43]
	v_cndmask_b32_e64 v76, v50, v58, s[42:43]
	v_mov_b32_e32 v77, v131
	s_nop 1
	v_mov_b32_dpp v77, v76 row_ror:8 row_mask:0xf bank_mask:0xf
	v_cndmask_b32_e64 v58, v58, v77, s[42:43]
	v_cndmask_b32_e64 v76, v77, v50, s[42:43]
	v_cndmask_b32_e64 v50, v51, v59, s[42:43]
	v_mov_b32_e32 v77, v131
	s_nop 1
	v_mov_b32_dpp v77, v50 row_ror:8 row_mask:0xf bank_mask:0xf
	v_cndmask_b32_e64 v59, v59, v77, s[42:43]
	v_cndmask_b32_e64 v77, v77, v51, s[42:43]
	v_cndmask_b32_e64 v50, v52, v60, s[42:43]
	v_mov_b32_e32 v51, v131
	s_nop 1
	v_mov_b32_dpp v51, v50 row_ror:8 row_mask:0xf bank_mask:0xf
	v_cndmask_b32_e64 v60, v60, v51, s[42:43]
	v_cndmask_b32_e64 v78, v51, v52, s[42:43]
	v_cndmask_b32_e64 v50, v53, v61, s[42:43]
	v_mov_b32_e32 v51, v131
	v_lshlrev_b32_e32 v52, 16, v162
	v_add_f32_e32 v83, v58, v52
	v_mov_b32_dpp v51, v50 row_ror:8 row_mask:0xf bank_mask:0xf
	v_cndmask_b32_e64 v61, v61, v51, s[42:43]
	v_cndmask_b32_e64 v53, v51, v53, s[42:43]
	v_lshlrev_b32_e32 v51, 16, v161
	v_add_f32_e32 v64, v64, v51
	v_and_b32_e32 v51, 0xffff0000, v161
	v_add_f32_e32 v65, v65, v51
	v_lshlrev_b32_e32 v51, 16, v157
	v_add_f32_e32 v81, v56, v51
	v_and_b32_e32 v51, 0xffff0000, v157
	v_lshlrev_b32_e32 v50, 16, v160
	v_add_f32_e32 v82, v57, v51
	v_lshlrev_b32_e32 v57, 16, v163
	v_add_f32_e32 v62, v62, v50
	v_and_b32_e32 v50, 0xffff0000, v160
	v_and_b32_e32 v52, 0xffff0000, v162
	v_add_f32_e32 v60, v60, v57
	v_and_b32_e32 v57, 0xffff0000, v163
	v_add_f32_e32 v63, v63, v50
	v_lshlrev_b32_e32 v50, 16, v156
	v_add_f32_e32 v84, v59, v52
	v_lshlrev_b32_e32 v52, 16, v158
	v_add_f32_e32 v61, v61, v57
	v_lshlrev_b32_e32 v57, 16, v159
	v_add_f32_e32 v79, v54, v50
	v_and_b32_e32 v50, 0xffff0000, v156
	v_add_f32_e32 v76, v76, v52
	v_and_b32_e32 v52, 0xffff0000, v158
	v_add_f32_e32 v78, v78, v57
	v_and_b32_e32 v57, 0xffff0000, v159
	v_lshl_add_u64 v[58:59], v[72:73], 1, s[36:37]
	v_add_f32_e32 v80, v55, v50
	v_cvt_pk_bf16_f32 v50, v62, v63
	v_cvt_pk_bf16_f32 v51, v64, v65
	v_add_f32_e32 v77, v77, v52
	v_cvt_pk_bf16_f32 v52, v83, v84
	v_add_f32_e32 v85, v53, v57
	v_cvt_pk_bf16_f32 v53, v60, v61
	v_lshl_add_u64 v[58:59], v[58:59], 0, v[204:205]
	global_store_dwordx4 v[58:59], v[50:53], off sc1
	v_cvt_pk_bf16_f32 v54, v79, v80
	v_cvt_pk_bf16_f32 v55, v81, v82
	v_add_co_u32_e32 v50, vcc, s97, v58
	v_cvt_pk_bf16_f32 v56, v76, v77
	v_cvt_pk_bf16_f32 v57, v78, v85
	v_addc_co_u32_e32 v51, vcc, 0, v59, vcc
	global_store_dwordx4 v[50:51], v[54:57], off sc1
	v_cndmask_b32_e64 v50, v38, v46, s[42:43]
	v_mov_b32_e32 v51, v131
	s_nop 1
	v_mov_b32_dpp v51, v50 row_ror:8 row_mask:0xf bank_mask:0xf
	v_cndmask_b32_e64 v46, v46, v51, s[42:43]
	v_cndmask_b32_e64 v38, v51, v38, s[42:43]
	v_cndmask_b32_e64 v50, v39, v47, s[42:43]
	v_mov_b32_e32 v51, v131
	s_nop 1
	v_mov_b32_dpp v51, v50 row_ror:8 row_mask:0xf bank_mask:0xf
	v_cndmask_b32_e64 v47, v47, v51, s[42:43]
	v_cndmask_b32_e64 v39, v51, v39, s[42:43]
	v_cndmask_b32_e64 v50, v40, v48, s[42:43]
	v_mov_b32_e32 v51, v131
	s_nop 1
	v_mov_b32_dpp v51, v50 row_ror:8 row_mask:0xf bank_mask:0xf
	v_cndmask_b32_e64 v48, v48, v51, s[42:43]
	v_cndmask_b32_e64 v40, v51, v40, s[42:43]
	v_cndmask_b32_e64 v50, v41, v49, s[42:43]
	v_mov_b32_e32 v51, v131
	s_nop 1
	v_mov_b32_dpp v51, v50 row_ror:8 row_mask:0xf bank_mask:0xf
	v_cndmask_b32_e64 v49, v49, v51, s[42:43]
	v_cndmask_b32_e64 v41, v51, v41, s[42:43]
	v_cndmask_b32_e64 v50, v34, v42, s[42:43]
	v_mov_b32_e32 v51, v131
	s_nop 1
	v_mov_b32_dpp v51, v50 row_ror:8 row_mask:0xf bank_mask:0xf
	v_cndmask_b32_e64 v52, v42, v51, s[42:43]
	v_cndmask_b32_e64 v53, v51, v34, s[42:43]
	v_cndmask_b32_e64 v34, v35, v43, s[42:43]
	v_mov_b32_e32 v42, v131
	s_nop 1
	v_mov_b32_dpp v42, v34 row_ror:8 row_mask:0xf bank_mask:0xf
	v_cndmask_b32_e64 v57, v42, v35, s[42:43]
	v_cndmask_b32_e64 v34, v36, v44, s[42:43]
	v_mov_b32_e32 v35, v131
	v_cndmask_b32_e64 v56, v43, v42, s[42:43]
	s_nop 0
	v_mov_b32_dpp v35, v34 row_ror:8 row_mask:0xf bank_mask:0xf
	v_cndmask_b32_e64 v44, v44, v35, s[42:43]
	v_cndmask_b32_e64 v58, v35, v36, s[42:43]
	v_cndmask_b32_e64 v34, v37, v45, s[42:43]
	v_mov_b32_e32 v35, v131
	s_nop 1
	v_mov_b32_dpp v35, v34 row_ror:8 row_mask:0xf bank_mask:0xf
	v_cndmask_b32_e64 v45, v45, v35, s[42:43]
	v_cndmask_b32_e64 v59, v35, v37, s[42:43]
	s_waitcnt vmcnt(15)
	v_and_b32_e32 v35, 0xffff0000, v148
	v_add_f32_e32 v36, v47, v35
	s_waitcnt vmcnt(14)
	v_lshlrev_b32_e32 v35, 16, v144
	v_and_b32_e32 v37, 0xffff0000, v144
	v_add_f32_e32 v35, v38, v35
	v_add_f32_e32 v39, v39, v37
	v_lshlrev_b32_e32 v37, 16, v149
	v_and_b32_e32 v38, 0xffff0000, v149
	v_add_f32_e32 v37, v48, v37
	v_add_f32_e32 v42, v49, v38
	v_lshlrev_b32_e32 v38, 16, v145
	v_lshlrev_b32_e32 v48, 16, v151
	v_add_f32_e32 v38, v40, v38
	v_and_b32_e32 v40, 0xffff0000, v145
	v_add_f32_e32 v44, v44, v48
	v_and_b32_e32 v48, 0xffff0000, v151
	v_lshlrev_b32_e32 v34, 16, v148
	v_add_f32_e32 v43, v41, v40
	v_lshlrev_b32_e32 v40, 16, v150
	v_and_b32_e32 v41, 0xffff0000, v150
	v_add_f32_e32 v48, v45, v48
	v_lshlrev_b32_e32 v45, 16, v147
	v_and_b32_e32 v49, 0xffff0000, v147
	v_add_f32_e32 v34, v46, v34
	v_add_f32_e32 v40, v52, v40
	v_add_f32_e32 v46, v56, v41
	v_lshlrev_b32_e32 v41, 16, v146
	v_add_f32_e32 v45, v58, v45
	v_add_f32_e32 v49, v59, v49
	v_lshl_add_u64 v[58:59], v[74:75], 1, s[36:37]
	v_cvt_pk_bf16_f32 v50, v34, v36
	v_cvt_pk_bf16_f32 v51, v37, v42
	v_add_f32_e32 v41, v53, v41
	v_and_b32_e32 v47, 0xffff0000, v146
	v_cvt_pk_bf16_f32 v52, v40, v46
	v_cvt_pk_bf16_f32 v53, v44, v48
	v_lshl_add_u64 v[58:59], v[58:59], 0, v[204:205]
	v_add_f32_e32 v47, v57, v47
	global_store_dwordx4 v[58:59], v[50:53], off sc1
	v_cvt_pk_bf16_f32 v54, v35, v39
	v_cvt_pk_bf16_f32 v55, v38, v43
	v_add_co_u32_e32 v50, vcc, s97, v58
	v_cvt_pk_bf16_f32 v56, v41, v47
	v_cvt_pk_bf16_f32 v57, v45, v49
	v_addc_co_u32_e32 v51, vcc, 0, v59, vcc
	global_store_dwordx4 v[50:51], v[54:57], off sc1
	v_cndmask_b32_e64 v50, v22, v30, s[42:43]
	v_mov_b32_e32 v51, v131
	s_nop 1
	v_mov_b32_dpp v51, v50 row_ror:8 row_mask:0xf bank_mask:0xf
	v_cndmask_b32_e64 v30, v30, v51, s[42:43]
	v_cndmask_b32_e64 v22, v51, v22, s[42:43]
	v_cndmask_b32_e64 v50, v23, v31, s[42:43]
	v_mov_b32_e32 v51, v131
	s_nop 1
	v_mov_b32_dpp v51, v50 row_ror:8 row_mask:0xf bank_mask:0xf
	v_cndmask_b32_e64 v31, v31, v51, s[42:43]
	v_cndmask_b32_e64 v23, v51, v23, s[42:43]
	v_cndmask_b32_e64 v50, v24, v32, s[42:43]
	v_mov_b32_e32 v51, v131
	s_nop 1
	v_mov_b32_dpp v51, v50 row_ror:8 row_mask:0xf bank_mask:0xf
	v_cndmask_b32_e64 v32, v32, v51, s[42:43]
	v_cndmask_b32_e64 v24, v51, v24, s[42:43]
	v_cndmask_b32_e64 v50, v25, v33, s[42:43]
	v_mov_b32_e32 v51, v131
	s_nop 1
	v_mov_b32_dpp v51, v50 row_ror:8 row_mask:0xf bank_mask:0xf
	v_cndmask_b32_e64 v33, v33, v51, s[42:43]
	v_cndmask_b32_e64 v25, v51, v25, s[42:43]
	v_cndmask_b32_e64 v50, v18, v26, s[42:43]
	v_mov_b32_e32 v51, v131
	s_nop 1
	v_mov_b32_dpp v51, v50 row_ror:8 row_mask:0xf bank_mask:0xf
	v_cndmask_b32_e64 v52, v26, v51, s[42:43]
	v_cndmask_b32_e64 v53, v51, v18, s[42:43]
	v_cndmask_b32_e64 v18, v19, v27, s[42:43]
	v_mov_b32_e32 v26, v131
	s_nop 1
	v_mov_b32_dpp v26, v18 row_ror:8 row_mask:0xf bank_mask:0xf
	v_cndmask_b32_e64 v57, v26, v19, s[42:43]
	v_cndmask_b32_e64 v18, v20, v28, s[42:43]
	v_mov_b32_e32 v19, v131
	v_cndmask_b32_e64 v56, v27, v26, s[42:43]
	s_nop 0
	v_mov_b32_dpp v19, v18 row_ror:8 row_mask:0xf bank_mask:0xf
	v_cndmask_b32_e64 v28, v28, v19, s[42:43]
	v_cndmask_b32_e64 v58, v19, v20, s[42:43]
	v_cndmask_b32_e64 v18, v21, v29, s[42:43]
	v_mov_b32_e32 v19, v131
	s_nop 1
	v_mov_b32_dpp v19, v18 row_ror:8 row_mask:0xf bank_mask:0xf
	v_cndmask_b32_e64 v29, v29, v19, s[42:43]
	v_cndmask_b32_e64 v59, v19, v21, s[42:43]
	s_waitcnt vmcnt(15)
	v_and_b32_e32 v19, 0xffff0000, v126
	v_add_f32_e32 v20, v31, v19
	s_waitcnt vmcnt(14)
	v_lshlrev_b32_e32 v19, 16, v122
	v_and_b32_e32 v21, 0xffff0000, v122
	v_add_f32_e32 v19, v22, v19
	v_add_f32_e32 v23, v23, v21
	v_lshlrev_b32_e32 v21, 16, v127
	v_and_b32_e32 v22, 0xffff0000, v127
	v_add_f32_e32 v21, v32, v21
	v_add_f32_e32 v26, v33, v22
	v_lshlrev_b32_e32 v22, 16, v123
	v_lshlrev_b32_e32 v32, 16, v129
	v_add_f32_e32 v22, v24, v22
	v_and_b32_e32 v24, 0xffff0000, v123
	v_add_f32_e32 v28, v28, v32
	v_and_b32_e32 v32, 0xffff0000, v129
	v_lshlrev_b32_e32 v18, 16, v126
	v_add_f32_e32 v27, v25, v24
	v_lshlrev_b32_e32 v24, 16, v128
	v_and_b32_e32 v25, 0xffff0000, v128
	v_add_f32_e32 v32, v29, v32
	v_lshlrev_b32_e32 v29, 16, v125
	v_and_b32_e32 v33, 0xffff0000, v125
	v_add_f32_e32 v18, v30, v18
	v_add_f32_e32 v24, v52, v24
	v_add_f32_e32 v30, v56, v25
	v_lshlrev_b32_e32 v25, 16, v124
	v_add_f32_e32 v29, v58, v29
	v_add_f32_e32 v33, v59, v33
	v_lshl_add_u64 v[58:59], v[68:69], 1, s[36:37]
	v_cvt_pk_bf16_f32 v50, v18, v20
	v_cvt_pk_bf16_f32 v51, v21, v26
	v_add_f32_e32 v25, v53, v25
	v_and_b32_e32 v31, 0xffff0000, v124
	v_cvt_pk_bf16_f32 v52, v24, v30
	v_cvt_pk_bf16_f32 v53, v28, v32
	v_lshl_add_u64 v[58:59], v[58:59], 0, v[204:205]
	v_add_f32_e32 v31, v57, v31
	global_store_dwordx4 v[58:59], v[50:53], off sc1
	v_cvt_pk_bf16_f32 v54, v19, v23
	v_cvt_pk_bf16_f32 v55, v22, v27
	v_add_co_u32_e32 v50, vcc, s97, v58
	v_cvt_pk_bf16_f32 v56, v25, v31
	v_cvt_pk_bf16_f32 v57, v29, v33
	v_addc_co_u32_e32 v51, vcc, 0, v59, vcc
	global_store_dwordx4 v[50:51], v[54:57], off sc1
	v_cndmask_b32_e64 v50, v6, v14, s[42:43]
	v_mov_b32_e32 v51, v131
	s_nop 1
	v_mov_b32_dpp v51, v50 row_ror:8 row_mask:0xf bank_mask:0xf
	v_cndmask_b32_e64 v14, v14, v51, s[42:43]
	v_cndmask_b32_e64 v6, v51, v6, s[42:43]
	v_cndmask_b32_e64 v50, v7, v15, s[42:43]
	v_mov_b32_e32 v51, v131
	s_nop 1
	v_mov_b32_dpp v51, v50 row_ror:8 row_mask:0xf bank_mask:0xf
	v_cndmask_b32_e64 v15, v15, v51, s[42:43]
	v_cndmask_b32_e64 v7, v51, v7, s[42:43]
	v_cndmask_b32_e64 v50, v8, v16, s[42:43]
	v_mov_b32_e32 v51, v131
	s_nop 1
	v_mov_b32_dpp v51, v50 row_ror:8 row_mask:0xf bank_mask:0xf
	v_cndmask_b32_e64 v16, v16, v51, s[42:43]
	v_cndmask_b32_e64 v8, v51, v8, s[42:43]
	v_cndmask_b32_e64 v50, v9, v17, s[42:43]
	v_mov_b32_e32 v51, v131
	s_nop 1
	v_mov_b32_dpp v51, v50 row_ror:8 row_mask:0xf bank_mask:0xf
	v_cndmask_b32_e64 v17, v17, v51, s[42:43]
	v_cndmask_b32_e64 v9, v51, v9, s[42:43]
	v_cndmask_b32_e64 v50, v2, v10, s[42:43]
	v_mov_b32_e32 v51, v131
	s_nop 1
	v_mov_b32_dpp v51, v50 row_ror:8 row_mask:0xf bank_mask:0xf
	v_cndmask_b32_e64 v52, v10, v51, s[42:43]
	v_cndmask_b32_e64 v53, v51, v2, s[42:43]
	v_cndmask_b32_e64 v2, v3, v11, s[42:43]
	v_mov_b32_e32 v10, v131
	s_nop 1
	v_mov_b32_dpp v10, v2 row_ror:8 row_mask:0xf bank_mask:0xf
	v_cndmask_b32_e64 v57, v10, v3, s[42:43]
	v_cndmask_b32_e64 v2, v4, v12, s[42:43]
	v_mov_b32_e32 v3, v131
	v_cndmask_b32_e64 v56, v11, v10, s[42:43]
	s_nop 0
	v_mov_b32_dpp v3, v2 row_ror:8 row_mask:0xf bank_mask:0xf
	v_cndmask_b32_e64 v12, v12, v3, s[42:43]
	v_cndmask_b32_e64 v58, v3, v4, s[42:43]
	v_cndmask_b32_e64 v2, v5, v13, s[42:43]
	v_mov_b32_e32 v3, v131
	s_nop 1
	v_mov_b32_dpp v3, v2 row_ror:8 row_mask:0xf bank_mask:0xf
	v_cndmask_b32_e64 v13, v13, v3, s[42:43]
	v_cndmask_b32_e64 v59, v3, v5, s[42:43]
	s_waitcnt vmcnt(15)
	v_and_b32_e32 v3, 0xffff0000, v102
	v_add_f32_e32 v4, v15, v3
	s_waitcnt vmcnt(14)
	v_lshlrev_b32_e32 v3, 16, v98
	v_and_b32_e32 v5, 0xffff0000, v98
	v_add_f32_e32 v3, v6, v3
	v_add_f32_e32 v7, v7, v5
	v_lshlrev_b32_e32 v5, 16, v103
	v_and_b32_e32 v6, 0xffff0000, v103
	v_add_f32_e32 v5, v16, v5
	v_add_f32_e32 v10, v17, v6
	v_lshlrev_b32_e32 v6, 16, v99
	v_lshlrev_b32_e32 v16, 16, v105
	v_add_f32_e32 v6, v8, v6
	v_and_b32_e32 v8, 0xffff0000, v99
	v_add_f32_e32 v12, v12, v16
	v_and_b32_e32 v16, 0xffff0000, v105
	v_lshlrev_b32_e32 v2, 16, v102
	v_add_f32_e32 v11, v9, v8
	v_lshlrev_b32_e32 v8, 16, v104
	v_and_b32_e32 v9, 0xffff0000, v104
	v_add_f32_e32 v16, v13, v16
	v_lshlrev_b32_e32 v13, 16, v101
	v_and_b32_e32 v17, 0xffff0000, v101
	v_add_f32_e32 v2, v14, v2
	v_add_f32_e32 v8, v52, v8
	v_add_f32_e32 v14, v56, v9
	v_lshlrev_b32_e32 v9, 16, v100
	v_add_f32_e32 v13, v58, v13
	v_add_f32_e32 v17, v59, v17
	v_lshl_add_u64 v[58:59], v[66:67], 1, s[36:37]
	v_cvt_pk_bf16_f32 v50, v2, v4
	v_cvt_pk_bf16_f32 v51, v5, v10
	v_add_f32_e32 v9, v53, v9
	v_and_b32_e32 v15, 0xffff0000, v100
	v_cvt_pk_bf16_f32 v52, v8, v14
	v_cvt_pk_bf16_f32 v53, v12, v16
	v_lshl_add_u64 v[58:59], v[58:59], 0, v[204:205]
	v_add_f32_e32 v15, v57, v15
	global_store_dwordx4 v[58:59], v[50:53], off sc1
	v_cvt_pk_bf16_f32 v54, v3, v7
	v_cvt_pk_bf16_f32 v55, v6, v11
	v_add_co_u32_e32 v50, vcc, s97, v58
	v_cvt_pk_bf16_f32 v56, v9, v15
	v_cvt_pk_bf16_f32 v57, v13, v17
	v_addc_co_u32_e32 v51, vcc, 0, v59, vcc
	global_store_dwordx4 v[50:51], v[54:57], off sc1
	v_mul_f32_e32 v50, v80, v80
	v_mul_f32_e32 v51, v82, v82
	v_fmac_f32_e32 v50, v79, v79
	v_fmac_f32_e32 v51, v81, v81
	v_add_f32_e32 v50, v50, v51
	v_mul_f32_e32 v51, v77, v77
	v_fmac_f32_e32 v51, v76, v76
	v_add_f32_e32 v50, v50, v51
	v_mul_f32_e32 v51, v85, v85
	v_fmac_f32_e32 v51, v78, v78
	v_add_f32_e32 v50, v50, v51
	v_mul_f32_e32 v51, v63, v63
	v_mul_f32_e32 v52, v65, v65
	v_fmac_f32_e32 v51, v62, v62
	v_fmac_f32_e32 v52, v64, v64
	v_add_f32_e32 v51, v51, v52
	v_mul_f32_e32 v52, v84, v84
	v_fmac_f32_e32 v52, v83, v83
	v_add_f32_e32 v51, v51, v52
	v_mul_f32_e32 v52, v61, v61
	v_fmac_f32_e32 v52, v60, v60
	v_add_f32_e32 v51, v51, v52
	s_nop 1
	v_add_f32_dpp v51, v51, v51 row_ror:8 row_mask:0xf bank_mask:0xf bound_ctrl:1
	v_add_f32_dpp v52, v50, v50 row_ror:8 row_mask:0xf bank_mask:0xf bound_ctrl:1
	ds_bpermute_b32 v50, v70, v51
	ds_bpermute_b32 v53, v70, v52
	s_waitcnt lgkmcnt(1)
	v_add_f32_e32 v50, v51, v50
	s_waitcnt lgkmcnt(0)
	v_add_f32_e32 v51, v52, v53
	ds_bpermute_b32 v52, v71, v50
	ds_bpermute_b32 v53, v71, v51
	s_and_saveexec_b64 s[28:29], s[56:57]
	s_cbranch_execz .LBB0_88
	s_waitcnt lgkmcnt(0)
	v_add_f32_e32 v53, v51, v53
	v_add_f32_e32 v52, v50, v52
	v_lshlrev_b64 v[50:51], 6, v[206:207]
	v_lshl_add_u64 v[50:51], s[52:53], 0, v[50:51]
	v_lshl_add_u64 v[50:51], s[60:61], 2, v[50:51]
	s_lshl_b32 s34, s72, 2
	v_lshl_add_u64 v[50:51], v[50:51], 0, s[34:35]
	global_store_dword v[50:51], v52, off sc1
	global_store_dword v[50:51], v53, off offset:512 sc1
.LBB0_88:
	s_or_b64 exec, exec, s[28:29]
	v_mul_f32_e32 v36, v36, v36
	v_fmac_f32_e32 v36, v34, v34
	v_mul_f32_e32 v34, v39, v39
	v_fmac_f32_e32 v34, v35, v35
	v_mul_f32_e32 v35, v42, v42
	v_fmac_f32_e32 v35, v37, v37
	v_add_f32_e32 v35, v36, v35
	v_mul_f32_e32 v36, v43, v43
	v_fmac_f32_e32 v36, v38, v38
	v_add_f32_e32 v34, v34, v36
	v_mul_f32_e32 v36, v46, v46
	v_fmac_f32_e32 v36, v40, v40
	v_add_f32_e32 v35, v35, v36
	v_mul_f32_e32 v36, v47, v47
	v_fmac_f32_e32 v36, v41, v41
	v_add_f32_e32 v34, v34, v36
	v_mul_f32_e32 v36, v48, v48
	v_fmac_f32_e32 v36, v44, v44
	v_add_f32_e32 v35, v35, v36
	v_mul_f32_e32 v36, v49, v49
	v_fmac_f32_e32 v36, v45, v45
	v_add_f32_e32 v34, v34, v36
	s_nop 1
	v_add_f32_dpp v35, v35, v35 row_ror:8 row_mask:0xf bank_mask:0xf bound_ctrl:1
	v_add_f32_dpp v36, v34, v34 row_ror:8 row_mask:0xf bank_mask:0xf bound_ctrl:1
	ds_bpermute_b32 v34, v70, v35
	ds_bpermute_b32 v37, v70, v36
	s_waitcnt lgkmcnt(1)
	v_add_f32_e32 v34, v35, v34
	s_waitcnt lgkmcnt(0)
	v_add_f32_e32 v35, v36, v37
	ds_bpermute_b32 v36, v71, v34
	ds_bpermute_b32 v37, v71, v35
	s_and_saveexec_b64 s[28:29], s[56:57]
	s_cbranch_execz .LBB0_90
	s_waitcnt lgkmcnt(0)
	v_add_f32_e32 v37, v35, v37
	v_add_f32_e32 v36, v34, v36
	v_lshlrev_b64 v[34:35], 6, v[202:203]
	v_lshl_add_u64 v[34:35], s[52:53], 0, v[34:35]
	v_lshl_add_u64 v[34:35], s[60:61], 2, v[34:35]
	s_lshl_b32 s34, s72, 2
	v_lshl_add_u64 v[34:35], v[34:35], 0, s[34:35]
	global_store_dword v[34:35], v36, off sc1
	global_store_dword v[34:35], v37, off offset:512 sc1
.LBB0_90:
	s_or_b64 exec, exec, s[28:29]
	v_mul_f32_e32 v20, v20, v20
	v_fmac_f32_e32 v20, v18, v18
	v_mul_f32_e32 v18, v23, v23
	v_fmac_f32_e32 v18, v19, v19
	v_mul_f32_e32 v19, v26, v26
	v_fmac_f32_e32 v19, v21, v21
	v_add_f32_e32 v19, v20, v19
	v_mul_f32_e32 v20, v27, v27
	v_fmac_f32_e32 v20, v22, v22
	v_add_f32_e32 v18, v18, v20
	v_mul_f32_e32 v20, v30, v30
	v_fmac_f32_e32 v20, v24, v24
	v_add_f32_e32 v19, v19, v20
	v_mul_f32_e32 v20, v31, v31
	v_fmac_f32_e32 v20, v25, v25
	v_add_f32_e32 v18, v18, v20
	v_mul_f32_e32 v20, v32, v32
	v_fmac_f32_e32 v20, v28, v28
	v_add_f32_e32 v19, v19, v20
	v_mul_f32_e32 v20, v33, v33
	v_fmac_f32_e32 v20, v29, v29
	v_add_f32_e32 v18, v18, v20
	s_nop 1
	v_add_f32_dpp v19, v19, v19 row_ror:8 row_mask:0xf bank_mask:0xf bound_ctrl:1
	v_add_f32_dpp v20, v18, v18 row_ror:8 row_mask:0xf bank_mask:0xf bound_ctrl:1
	ds_bpermute_b32 v18, v70, v19
	ds_bpermute_b32 v21, v70, v20
	s_waitcnt lgkmcnt(1)
	v_add_f32_e32 v18, v19, v18
	s_waitcnt lgkmcnt(0)
	v_add_f32_e32 v19, v20, v21
	ds_bpermute_b32 v20, v71, v18
	ds_bpermute_b32 v21, v71, v19
	s_and_saveexec_b64 s[28:29], s[56:57]
	s_cbranch_execz .LBB0_92
	s_waitcnt lgkmcnt(0)
	v_add_f32_e32 v21, v19, v21
	v_add_f32_e32 v20, v18, v20
	v_lshlrev_b64 v[18:19], 6, v[200:201]
	v_lshl_add_u64 v[18:19], s[52:53], 0, v[18:19]
	v_lshl_add_u64 v[18:19], s[60:61], 2, v[18:19]
	s_lshl_b32 s34, s72, 2
	v_lshl_add_u64 v[18:19], v[18:19], 0, s[34:35]
	global_store_dword v[18:19], v20, off sc1
	global_store_dword v[18:19], v21, off offset:512 sc1
.LBB0_92:
	s_or_b64 exec, exec, s[28:29]
	v_mul_f32_e32 v4, v4, v4
	v_fmac_f32_e32 v4, v2, v2
	v_mul_f32_e32 v2, v7, v7
	v_fmac_f32_e32 v2, v3, v3
	v_mul_f32_e32 v3, v10, v10
	v_fmac_f32_e32 v3, v5, v5
	v_add_f32_e32 v3, v4, v3
	v_mul_f32_e32 v4, v11, v11
	v_fmac_f32_e32 v4, v6, v6
	v_add_f32_e32 v2, v2, v4
	v_mul_f32_e32 v4, v14, v14
	v_fmac_f32_e32 v4, v8, v8
	v_add_f32_e32 v3, v3, v4
	v_mul_f32_e32 v4, v15, v15
	v_fmac_f32_e32 v4, v9, v9
	v_add_f32_e32 v2, v2, v4
	v_mul_f32_e32 v4, v16, v16
	v_fmac_f32_e32 v4, v12, v12
	v_add_f32_e32 v3, v3, v4
	v_mul_f32_e32 v4, v17, v17
	v_fmac_f32_e32 v4, v13, v13
	v_add_f32_e32 v2, v2, v4
	s_nop 1
	v_add_f32_dpp v3, v3, v3 row_ror:8 row_mask:0xf bank_mask:0xf bound_ctrl:1
	v_add_f32_dpp v4, v2, v2 row_ror:8 row_mask:0xf bank_mask:0xf bound_ctrl:1
	ds_bpermute_b32 v2, v70, v3
	ds_bpermute_b32 v5, v70, v4
	s_waitcnt lgkmcnt(1)
	v_add_f32_e32 v2, v3, v2
	s_waitcnt lgkmcnt(0)
	v_add_f32_e32 v3, v4, v5
	ds_bpermute_b32 v4, v71, v2
	ds_bpermute_b32 v5, v71, v3
	s_and_saveexec_b64 s[28:29], s[56:57]
	s_cbranch_execz .LBB0_94
	s_waitcnt lgkmcnt(0)
	v_add_f32_e32 v5, v3, v5
	v_add_f32_e32 v4, v2, v4
	v_lshlrev_b64 v[2:3], 6, v[198:199]
	v_lshl_add_u64 v[2:3], s[52:53], 0, v[2:3]
	v_lshl_add_u64 v[2:3], s[60:61], 2, v[2:3]
	s_lshl_b32 s34, s72, 2
	v_lshl_add_u64 v[2:3], v[2:3], 0, s[34:35]
	global_store_dword v[2:3], v4, off sc1
	global_store_dword v[2:3], v5, off offset:512 sc1

.LBB0_500:
	v_lshl_add_u32 v146, s6, 8, v142
	s_sub_i32 s6, s6, s5
	v_lshl_add_u32 v147, s6, 10, v143
	ds_read2_b32 v[150:151], v147 offset1:16
	v_lshl_or_b32 v148, s7, 8, v144
	v_ashrrev_i32_e32 v149, 31, v148
	s_mov_b32 s8, 0xc000
	s_mov_b64 s[28:29], -1
	s_waitcnt lgkmcnt(0)
	v_pk_mul_f32 v[126:127], v[126:127], v[150:151] op_sel_hi:[1,0]
	v_pk_mul_f32 v[118:119], v[118:119], v[150:151] op_sel_hi:[1,0]
	v_cvt_pk_bf16_f32 v152, v126, v127
	v_pk_mul_f32 v[126:127], v[128:129], v[150:151] op_sel_hi:[1,0]
	v_pk_mul_f32 v[114:115], v[114:115], v[150:151] op_sel_hi:[1,0]
	v_cvt_pk_bf16_f32 v126, v126, v127
	v_cvt_pk_bf16_f32 v127, v118, v119
	v_pk_mul_f32 v[118:119], v[120:121], v[150:151] op_sel_hi:[1,0]
	v_cvt_pk_bf16_f32 v120, v118, v119
	v_pk_mul_f32 v[118:119], v[122:123], v[150:151] op_sel_hi:[1,0]
	v_cvt_pk_bf16_f32 v121, v118, v119
	v_pk_mul_f32 v[118:119], v[124:125], v[150:151] op_sel_hi:[1,0]
	v_cvt_pk_bf16_f32 v124, v114, v115
	v_pk_mul_f32 v[114:115], v[116:117], v[150:151] op_sel_hi:[1,0]
	v_mov_b32_e32 v116, 0
	v_cvt_pk_bf16_f32 v114, v114, v115
	v_cndmask_b32_e64 v115, v127, v152, s[42:43]
	v_cvt_pk_bf16_f32 v125, v118, v119
	s_nop 0
	v_mov_b32_dpp v116, v115 row_ror:8 row_mask:0xf bank_mask:0xf
	v_cndmask_b32_e64 v118, v152, v116, s[42:43]
	v_cndmask_b32_e64 v122, v116, v127, s[42:43]
	v_cndmask_b32_e64 v115, v120, v126, s[42:43]
	v_mov_b32_e32 v116, 0
	s_nop 1
	v_mov_b32_dpp v116, v115 row_ror:8 row_mask:0xf bank_mask:0xf
	v_cndmask_b32_e64 v119, v126, v116, s[42:43]
	v_cndmask_b32_e64 v123, v116, v120, s[42:43]
	v_cndmask_b32_e64 v115, v124, v121, s[42:43]
	v_mov_b32_e32 v116, 0
	s_nop 1
	v_mov_b32_dpp v116, v115 row_ror:8 row_mask:0xf bank_mask:0xf
	v_cndmask_b32_e64 v120, v121, v116, s[42:43]
	v_cndmask_b32_e64 v124, v116, v124, s[42:43]
	v_cndmask_b32_e64 v115, v114, v125, s[42:43]
	v_mov_b32_e32 v116, 0
	s_nop 1
	v_mov_b32_dpp v116, v115 row_ror:8 row_mask:0xf bank_mask:0xf
	v_cndmask_b32_e64 v121, v125, v116, s[42:43]
	v_cndmask_b32_e64 v125, v116, v114, s[42:43]
	v_mov_b64_e32 v[114:115], s[80:81]
	v_mad_i64_i32 v[126:127], s[6:7], v146, s87, v[114:115]
	v_lshlrev_b64 v[116:117], 1, v[148:149]
	v_lshl_add_u64 v[126:127], v[126:127], 0, v[116:117]
	global_store_dwordx4 v[126:127], v[118:121], off sc1
	s_nop 1
	v_add_co_u32_e32 v118, vcc, s8, v126
	s_nop 1
	v_addc_co_u32_e32 v119, vcc, 0, v127, vcc
	global_store_dwordx4 v[118:119], v[122:125], off sc1
	v_mov_b32_e32 v118, v151
	v_pk_mul_f32 v[110:111], v[110:111], v[118:119] op_sel_hi:[1,0]
	v_cvt_pk_bf16_f32 v119, v110, v111
	v_pk_mul_f32 v[110:111], v[112:113], v[118:119] op_sel_hi:[1,0]
	v_pk_mul_f32 v[102:103], v[102:103], v[118:119] op_sel_hi:[1,0]
	v_cvt_pk_bf16_f32 v110, v110, v111
	v_cvt_pk_bf16_f32 v111, v102, v103
	v_pk_mul_f32 v[102:103], v[104:105], v[118:119] op_sel_hi:[1,0]
	v_pk_mul_f32 v[98:99], v[98:99], v[118:119] op_sel_hi:[1,0]
	v_cvt_pk_bf16_f32 v104, v102, v103
	v_pk_mul_f32 v[102:103], v[106:107], v[118:119] op_sel_hi:[1,0]
	v_cvt_pk_bf16_f32 v107, v98, v99
	v_pk_mul_f32 v[98:99], v[100:101], v[118:119] op_sel_hi:[1,0]
	v_cvt_pk_bf16_f32 v105, v102, v103
	v_pk_mul_f32 v[102:103], v[108:109], v[118:119] op_sel_hi:[1,0]
	v_cvt_pk_bf16_f32 v108, v98, v99
	v_cndmask_b32_e64 v98, v111, v119, s[42:43]
	v_mov_b32_e32 v99, 0
	v_cvt_pk_bf16_f32 v106, v102, v103
	v_mov_b32_e32 v100, 0
	v_mov_b32_dpp v99, v98 row_ror:8 row_mask:0xf bank_mask:0xf
	v_cndmask_b32_e64 v98, v119, v99, s[42:43]
	v_cndmask_b32_e64 v102, v99, v111, s[42:43]
	v_cndmask_b32_e64 v99, v104, v110, s[42:43]
	v_mov_b32_e32 v101, 0
	s_nop 0
	v_mov_b32_dpp v100, v99 row_ror:8 row_mask:0xf bank_mask:0xf
	v_cndmask_b32_e64 v99, v110, v100, s[42:43]
	v_cndmask_b32_e64 v103, v100, v104, s[42:43]
	v_cndmask_b32_e64 v100, v107, v105, s[42:43]
	s_nop 1
	v_mov_b32_dpp v101, v100 row_ror:8 row_mask:0xf bank_mask:0xf
	v_cndmask_b32_e64 v100, v105, v101, s[42:43]
	v_cndmask_b32_e64 v104, v101, v107, s[42:43]
	v_cndmask_b32_e64 v101, v108, v106, s[42:43]
	v_mov_b32_e32 v105, 0
	s_nop 1
	v_mov_b32_dpp v105, v101 row_ror:8 row_mask:0xf bank_mask:0xf
	v_cndmask_b32_e64 v101, v106, v105, s[42:43]
	v_or_b32_e32 v106, 16, v146
	v_mad_i64_i32 v[106:107], s[6:7], v106, s87, v[114:115]
	v_lshl_add_u64 v[106:107], v[106:107], 0, v[116:117]
	global_store_dwordx4 v[106:107], v[98:101], off sc1
	v_cndmask_b32_e64 v105, v105, v108, s[42:43]
	s_nop 0
	v_add_co_u32_e32 v98, vcc, s8, v106
	s_nop 1
	v_addc_co_u32_e32 v99, vcc, 0, v107, vcc
	global_store_dwordx4 v[98:99], v[102:105], off sc1
	ds_read2_b32 v[98:99], v147 offset0:32 offset1:48
	s_waitcnt lgkmcnt(0)
	v_pk_mul_f32 v[94:95], v[94:95], v[98:99] op_sel_hi:[1,0]
	v_cvt_pk_bf16_f32 v100, v94, v95
	v_pk_mul_f32 v[94:95], v[96:97], v[98:99] op_sel_hi:[1,0]
	v_pk_mul_f32 v[86:87], v[86:87], v[98:99] op_sel_hi:[1,0]
	v_cvt_pk_bf16_f32 v94, v94, v95
	v_cvt_pk_bf16_f32 v95, v86, v87
	v_pk_mul_f32 v[86:87], v[88:89], v[98:99] op_sel_hi:[1,0]
	v_pk_mul_f32 v[82:83], v[82:83], v[98:99] op_sel_hi:[1,0]
	v_cvt_pk_bf16_f32 v88, v86, v87
	v_pk_mul_f32 v[86:87], v[90:91], v[98:99] op_sel_hi:[1,0]
	v_cvt_pk_bf16_f32 v91, v82, v83
	v_pk_mul_f32 v[82:83], v[84:85], v[98:99] op_sel_hi:[1,0]
	v_cvt_pk_bf16_f32 v89, v86, v87
	v_pk_mul_f32 v[86:87], v[92:93], v[98:99] op_sel_hi:[1,0]
	v_cvt_pk_bf16_f32 v92, v82, v83
	v_cndmask_b32_e64 v82, v95, v100, s[42:43]
	v_mov_b32_e32 v83, 0
	v_cvt_pk_bf16_f32 v90, v86, v87
	v_mov_b32_e32 v84, 0
	v_mov_b32_dpp v83, v82 row_ror:8 row_mask:0xf bank_mask:0xf
	v_cndmask_b32_e64 v82, v100, v83, s[42:43]
	v_cndmask_b32_e64 v86, v83, v95, s[42:43]
	v_cndmask_b32_e64 v83, v88, v94, s[42:43]
	v_mov_b32_e32 v85, 0
	s_nop 0
	v_mov_b32_dpp v84, v83 row_ror:8 row_mask:0xf bank_mask:0xf
	v_cndmask_b32_e64 v83, v94, v84, s[42:43]
	v_cndmask_b32_e64 v87, v84, v88, s[42:43]
	v_cndmask_b32_e64 v84, v91, v89, s[42:43]
	s_nop 1
	v_mov_b32_dpp v85, v84 row_ror:8 row_mask:0xf bank_mask:0xf
	v_cndmask_b32_e64 v84, v89, v85, s[42:43]
	v_cndmask_b32_e64 v88, v85, v91, s[42:43]
	v_cndmask_b32_e64 v85, v92, v90, s[42:43]
	v_mov_b32_e32 v89, 0
	s_nop 1
	v_mov_b32_dpp v89, v85 row_ror:8 row_mask:0xf bank_mask:0xf
	v_cndmask_b32_e64 v85, v90, v89, s[42:43]
	v_or_b32_e32 v90, 32, v146
	v_mad_i64_i32 v[90:91], s[6:7], v90, s87, v[114:115]
	v_lshl_add_u64 v[90:91], v[90:91], 0, v[116:117]
	global_store_dwordx4 v[90:91], v[82:85], off sc1
	v_cndmask_b32_e64 v89, v89, v92, s[42:43]
	s_nop 0
	v_add_co_u32_e32 v82, vcc, s8, v90
	s_nop 1
	v_addc_co_u32_e32 v83, vcc, 0, v91, vcc
	global_store_dwordx4 v[82:83], v[86:89], off sc1
	v_mov_b32_e32 v82, v99
	v_pk_mul_f32 v[78:79], v[78:79], v[82:83] op_sel_hi:[1,0]
	v_cvt_pk_bf16_f32 v83, v78, v79
	v_pk_mul_f32 v[78:79], v[80:81], v[82:83] op_sel_hi:[1,0]
	v_pk_mul_f32 v[70:71], v[70:71], v[82:83] op_sel_hi:[1,0]
	v_cvt_pk_bf16_f32 v78, v78, v79
	v_cvt_pk_bf16_f32 v79, v70, v71
	v_pk_mul_f32 v[70:71], v[72:73], v[82:83] op_sel_hi:[1,0]
	v_pk_mul_f32 v[66:67], v[66:67], v[82:83] op_sel_hi:[1,0]
	v_cvt_pk_bf16_f32 v72, v70, v71
	v_pk_mul_f32 v[70:71], v[74:75], v[82:83] op_sel_hi:[1,0]
	v_cvt_pk_bf16_f32 v75, v66, v67
	v_pk_mul_f32 v[66:67], v[68:69], v[82:83] op_sel_hi:[1,0]
	v_cvt_pk_bf16_f32 v73, v70, v71
	v_pk_mul_f32 v[70:71], v[76:77], v[82:83] op_sel_hi:[1,0]
	v_cvt_pk_bf16_f32 v76, v66, v67
	v_cndmask_b32_e64 v66, v79, v83, s[42:43]
	v_mov_b32_e32 v67, 0
	v_cvt_pk_bf16_f32 v74, v70, v71
	v_mov_b32_e32 v68, 0
	v_mov_b32_dpp v67, v66 row_ror:8 row_mask:0xf bank_mask:0xf
	v_cndmask_b32_e64 v66, v83, v67, s[42:43]
	v_cndmask_b32_e64 v70, v67, v79, s[42:43]
	v_cndmask_b32_e64 v67, v72, v78, s[42:43]
	v_mov_b32_e32 v69, 0
	s_nop 0
	v_mov_b32_dpp v68, v67 row_ror:8 row_mask:0xf bank_mask:0xf
	v_cndmask_b32_e64 v67, v78, v68, s[42:43]
	v_cndmask_b32_e64 v71, v68, v72, s[42:43]
	v_cndmask_b32_e64 v68, v75, v73, s[42:43]
	s_nop 1
	v_mov_b32_dpp v69, v68 row_ror:8 row_mask:0xf bank_mask:0xf
	v_cndmask_b32_e64 v68, v73, v69, s[42:43]
	v_cndmask_b32_e64 v72, v69, v75, s[42:43]
	v_cndmask_b32_e64 v69, v76, v74, s[42:43]
	v_mov_b32_e32 v73, 0
	s_nop 1
	v_mov_b32_dpp v73, v69 row_ror:8 row_mask:0xf bank_mask:0xf
	v_cndmask_b32_e64 v69, v74, v73, s[42:43]
	v_or_b32_e32 v74, 48, v146
	v_mad_i64_i32 v[74:75], s[6:7], v74, s87, v[114:115]
	v_lshl_add_u64 v[74:75], v[74:75], 0, v[116:117]
	global_store_dwordx4 v[74:75], v[66:69], off sc1
	v_cndmask_b32_e64 v73, v73, v76, s[42:43]
	s_nop 0
	v_add_co_u32_e32 v66, vcc, s8, v74
	s_nop 1
	v_addc_co_u32_e32 v67, vcc, 0, v75, vcc
	global_store_dwordx4 v[66:67], v[70:73], off sc1
	ds_read2_b32 v[66:67], v147 offset0:128 offset1:144
	s_waitcnt lgkmcnt(0)
	v_pk_mul_f32 v[62:63], v[62:63], v[66:67] op_sel_hi:[1,0]
	v_cvt_pk_bf16_f32 v68, v62, v63
	v_pk_mul_f32 v[62:63], v[64:65], v[66:67] op_sel_hi:[1,0]
	v_pk_mul_f32 v[54:55], v[54:55], v[66:67] op_sel_hi:[1,0]
	v_cvt_pk_bf16_f32 v62, v62, v63
	v_cvt_pk_bf16_f32 v63, v54, v55
	v_pk_mul_f32 v[54:55], v[56:57], v[66:67] op_sel_hi:[1,0]
	v_pk_mul_f32 v[50:51], v[50:51], v[66:67] op_sel_hi:[1,0]
	v_cvt_pk_bf16_f32 v56, v54, v55
	v_pk_mul_f32 v[54:55], v[58:59], v[66:67] op_sel_hi:[1,0]
	v_cvt_pk_bf16_f32 v59, v50, v51
	v_pk_mul_f32 v[50:51], v[52:53], v[66:67] op_sel_hi:[1,0]
	v_cvt_pk_bf16_f32 v57, v54, v55
	v_pk_mul_f32 v[54:55], v[60:61], v[66:67] op_sel_hi:[1,0]
	v_cvt_pk_bf16_f32 v60, v50, v51
	v_cndmask_b32_e64 v50, v63, v68, s[42:43]
	v_mov_b32_e32 v51, 0
	v_cvt_pk_bf16_f32 v58, v54, v55
	v_mov_b32_e32 v52, 0
	v_mov_b32_dpp v51, v50 row_ror:8 row_mask:0xf bank_mask:0xf
	v_cndmask_b32_e64 v50, v68, v51, s[42:43]
	v_cndmask_b32_e64 v54, v51, v63, s[42:43]
	v_cndmask_b32_e64 v51, v56, v62, s[42:43]
	v_mov_b32_e32 v53, 0
	s_nop 0
	v_mov_b32_dpp v52, v51 row_ror:8 row_mask:0xf bank_mask:0xf
	v_cndmask_b32_e64 v51, v62, v52, s[42:43]
	v_cndmask_b32_e64 v55, v52, v56, s[42:43]
	v_cndmask_b32_e64 v52, v59, v57, s[42:43]
	s_nop 1
	v_mov_b32_dpp v53, v52 row_ror:8 row_mask:0xf bank_mask:0xf
	v_cndmask_b32_e64 v52, v57, v53, s[42:43]
	v_cndmask_b32_e64 v56, v53, v59, s[42:43]
	v_cndmask_b32_e64 v53, v60, v58, s[42:43]
	v_mov_b32_e32 v57, 0
	s_nop 1
	v_mov_b32_dpp v57, v53 row_ror:8 row_mask:0xf bank_mask:0xf
	v_cndmask_b32_e64 v53, v58, v57, s[42:43]
	v_add_u32_e32 v58, 0x80, v146
	v_mad_i64_i32 v[58:59], s[6:7], v58, s87, v[114:115]
	v_lshl_add_u64 v[58:59], v[58:59], 0, v[116:117]
	global_store_dwordx4 v[58:59], v[50:53], off sc1
	v_cndmask_b32_e64 v57, v57, v60, s[42:43]
	s_nop 0
	v_add_co_u32_e32 v50, vcc, s8, v58
	s_nop 1
	v_addc_co_u32_e32 v51, vcc, 0, v59, vcc
	global_store_dwordx4 v[50:51], v[54:57], off sc1
	v_mov_b32_e32 v50, v67
	v_pk_mul_f32 v[46:47], v[46:47], v[50:51] op_sel_hi:[1,0]
	v_cvt_pk_bf16_f32 v51, v46, v47
	v_pk_mul_f32 v[46:47], v[48:49], v[50:51] op_sel_hi:[1,0]
	v_pk_mul_f32 v[38:39], v[38:39], v[50:51] op_sel_hi:[1,0]
	v_cvt_pk_bf16_f32 v46, v46, v47
	v_cvt_pk_bf16_f32 v47, v38, v39
	v_pk_mul_f32 v[38:39], v[40:41], v[50:51] op_sel_hi:[1,0]
	v_pk_mul_f32 v[34:35], v[34:35], v[50:51] op_sel_hi:[1,0]
	v_cvt_pk_bf16_f32 v40, v38, v39
	v_pk_mul_f32 v[38:39], v[42:43], v[50:51] op_sel_hi:[1,0]
	v_cvt_pk_bf16_f32 v43, v34, v35
	v_pk_mul_f32 v[34:35], v[36:37], v[50:51] op_sel_hi:[1,0]
	v_cvt_pk_bf16_f32 v41, v38, v39
	v_pk_mul_f32 v[38:39], v[44:45], v[50:51] op_sel_hi:[1,0]
	v_cvt_pk_bf16_f32 v44, v34, v35
	v_cndmask_b32_e64 v34, v47, v51, s[42:43]
	v_mov_b32_e32 v35, 0
	v_cvt_pk_bf16_f32 v42, v38, v39
	v_mov_b32_e32 v36, 0
	v_mov_b32_dpp v35, v34 row_ror:8 row_mask:0xf bank_mask:0xf
	v_cndmask_b32_e64 v34, v51, v35, s[42:43]
	v_cndmask_b32_e64 v38, v35, v47, s[42:43]
	v_cndmask_b32_e64 v35, v40, v46, s[42:43]
	v_mov_b32_e32 v37, 0
	s_nop 0
	v_mov_b32_dpp v36, v35 row_ror:8 row_mask:0xf bank_mask:0xf
	v_cndmask_b32_e64 v35, v46, v36, s[42:43]
	v_cndmask_b32_e64 v39, v36, v40, s[42:43]
	v_cndmask_b32_e64 v36, v43, v41, s[42:43]
	s_nop 1
	v_mov_b32_dpp v37, v36 row_ror:8 row_mask:0xf bank_mask:0xf
	v_cndmask_b32_e64 v36, v41, v37, s[42:43]
	v_cndmask_b32_e64 v40, v37, v43, s[42:43]
	v_cndmask_b32_e64 v37, v44, v42, s[42:43]
	v_mov_b32_e32 v41, 0
	s_nop 1
	v_mov_b32_dpp v41, v37 row_ror:8 row_mask:0xf bank_mask:0xf
	v_cndmask_b32_e64 v37, v42, v41, s[42:43]
	v_add_u32_e32 v42, 0x90, v146
	v_mad_i64_i32 v[42:43], s[6:7], v42, s87, v[114:115]
	v_lshl_add_u64 v[42:43], v[42:43], 0, v[116:117]
	global_store_dwordx4 v[42:43], v[34:37], off sc1
	v_cndmask_b32_e64 v41, v41, v44, s[42:43]
	s_nop 0
	v_add_co_u32_e32 v34, vcc, s8, v42
	s_nop 1
	v_addc_co_u32_e32 v35, vcc, 0, v43, vcc
	global_store_dwordx4 v[34:35], v[38:41], off sc1
	ds_read2_b32 v[34:35], v147 offset0:160 offset1:176
	s_waitcnt lgkmcnt(0)
	v_pk_mul_f32 v[30:31], v[30:31], v[34:35] op_sel_hi:[1,0]
	v_cvt_pk_bf16_f32 v36, v30, v31
	v_pk_mul_f32 v[30:31], v[32:33], v[34:35] op_sel_hi:[1,0]
	v_pk_mul_f32 v[22:23], v[22:23], v[34:35] op_sel_hi:[1,0]
	v_cvt_pk_bf16_f32 v30, v30, v31
	v_cvt_pk_bf16_f32 v31, v22, v23
	v_pk_mul_f32 v[22:23], v[24:25], v[34:35] op_sel_hi:[1,0]
	v_pk_mul_f32 v[18:19], v[18:19], v[34:35] op_sel_hi:[1,0]
	v_cvt_pk_bf16_f32 v24, v22, v23
	v_pk_mul_f32 v[22:23], v[26:27], v[34:35] op_sel_hi:[1,0]
	v_cvt_pk_bf16_f32 v27, v18, v19
	v_pk_mul_f32 v[18:19], v[20:21], v[34:35] op_sel_hi:[1,0]
	v_cvt_pk_bf16_f32 v25, v22, v23
	v_pk_mul_f32 v[22:23], v[28:29], v[34:35] op_sel_hi:[1,0]
	v_cvt_pk_bf16_f32 v28, v18, v19
	v_cndmask_b32_e64 v18, v31, v36, s[42:43]
	v_mov_b32_e32 v19, 0
	v_cvt_pk_bf16_f32 v26, v22, v23
	v_mov_b32_e32 v20, 0
	v_mov_b32_dpp v19, v18 row_ror:8 row_mask:0xf bank_mask:0xf
	v_cndmask_b32_e64 v18, v36, v19, s[42:43]
	v_cndmask_b32_e64 v22, v19, v31, s[42:43]
	v_cndmask_b32_e64 v19, v24, v30, s[42:43]
	v_mov_b32_e32 v21, 0
	s_nop 0
	v_mov_b32_dpp v20, v19 row_ror:8 row_mask:0xf bank_mask:0xf
	v_cndmask_b32_e64 v19, v30, v20, s[42:43]
	v_cndmask_b32_e64 v23, v20, v24, s[42:43]
	v_cndmask_b32_e64 v20, v27, v25, s[42:43]
	s_nop 1
	v_mov_b32_dpp v21, v20 row_ror:8 row_mask:0xf bank_mask:0xf
	v_cndmask_b32_e64 v20, v25, v21, s[42:43]
	v_cndmask_b32_e64 v24, v21, v27, s[42:43]
	v_cndmask_b32_e64 v21, v28, v26, s[42:43]
	v_mov_b32_e32 v25, 0
	s_nop 1
	v_mov_b32_dpp v25, v21 row_ror:8 row_mask:0xf bank_mask:0xf
	v_cndmask_b32_e64 v21, v26, v25, s[42:43]
	v_add_u32_e32 v26, 0xa0, v146
	v_mad_i64_i32 v[26:27], s[6:7], v26, s87, v[114:115]
	v_lshl_add_u64 v[26:27], v[26:27], 0, v[116:117]
	global_store_dwordx4 v[26:27], v[18:21], off sc1
	v_cndmask_b32_e64 v25, v25, v28, s[42:43]
	s_nop 0
	v_add_co_u32_e32 v18, vcc, s8, v26
	s_nop 1
	v_addc_co_u32_e32 v19, vcc, 0, v27, vcc
	global_store_dwordx4 v[18:19], v[22:25], off sc1
	v_mov_b32_e32 v18, v35
	v_pk_mul_f32 v[14:15], v[14:15], v[18:19] op_sel_hi:[1,0]
	v_cvt_pk_bf16_f32 v19, v14, v15
	v_pk_mul_f32 v[14:15], v[16:17], v[18:19] op_sel_hi:[1,0]
	v_pk_mul_f32 v[6:7], v[6:7], v[18:19] op_sel_hi:[1,0]
	v_cvt_pk_bf16_f32 v14, v14, v15
	v_cvt_pk_bf16_f32 v15, v6, v7
	v_pk_mul_f32 v[6:7], v[8:9], v[18:19] op_sel_hi:[1,0]
	v_pk_mul_f32 v[2:3], v[2:3], v[18:19] op_sel_hi:[1,0]
	v_cvt_pk_bf16_f32 v8, v6, v7
	v_pk_mul_f32 v[6:7], v[10:11], v[18:19] op_sel_hi:[1,0]
	v_cvt_pk_bf16_f32 v11, v2, v3
	v_pk_mul_f32 v[2:3], v[4:5], v[18:19] op_sel_hi:[1,0]
	v_cvt_pk_bf16_f32 v9, v6, v7
	v_pk_mul_f32 v[6:7], v[12:13], v[18:19] op_sel_hi:[1,0]
	v_cvt_pk_bf16_f32 v12, v2, v3
	v_cndmask_b32_e64 v2, v15, v19, s[42:43]
	v_mov_b32_e32 v3, 0
	v_cvt_pk_bf16_f32 v10, v6, v7
	v_mov_b32_e32 v4, 0
	v_mov_b32_dpp v3, v2 row_ror:8 row_mask:0xf bank_mask:0xf
	v_cndmask_b32_e64 v2, v19, v3, s[42:43]
	v_cndmask_b32_e64 v6, v3, v15, s[42:43]
	v_cndmask_b32_e64 v3, v8, v14, s[42:43]
	v_mov_b32_e32 v5, 0
	s_nop 0
	v_mov_b32_dpp v4, v3 row_ror:8 row_mask:0xf bank_mask:0xf
	v_cndmask_b32_e64 v3, v14, v4, s[42:43]
	v_cndmask_b32_e64 v7, v4, v8, s[42:43]
	v_cndmask_b32_e64 v4, v11, v9, s[42:43]
	s_nop 1
	v_mov_b32_dpp v5, v4 row_ror:8 row_mask:0xf bank_mask:0xf
	v_cndmask_b32_e64 v4, v9, v5, s[42:43]
	v_cndmask_b32_e64 v8, v5, v11, s[42:43]
	v_cndmask_b32_e64 v5, v12, v10, s[42:43]
	v_mov_b32_e32 v9, 0
	s_nop 1
	v_mov_b32_dpp v9, v5 row_ror:8 row_mask:0xf bank_mask:0xf
	v_cndmask_b32_e64 v5, v10, v9, s[42:43]
	v_add_u32_e32 v10, 0xb0, v146
	v_mad_i64_i32 v[10:11], s[6:7], v10, s87, v[114:115]
	v_lshl_add_u64 v[10:11], v[10:11], 0, v[116:117]
	global_store_dwordx4 v[10:11], v[2:5], off sc1
	v_cndmask_b32_e64 v9, v9, v12, s[42:43]
	s_nop 0
	v_add_co_u32_e32 v2, vcc, 0xc000, v10
	s_nop 1
	v_addc_co_u32_e32 v3, vcc, 0, v11, vcc
	s_andn2_b64 vcc, exec, s[44:45]
	global_store_dwordx4 v[2:3], v[6:9], off sc1
	s_cbranch_vccnz .LBB0_493
	s_andn2_b64 vcc, exec, s[48:49]
	s_cbranch_vccnz .LBB0_492
	s_barrier
	s_branch .LBB0_492
